# speedup vs baseline: 1.0072x; 1.0064x over previous
; __device__ __forceinline__ void gmlp_item(PARAMS_T& p, int l, int b, int pos0, int tokrow0) {
;     ...
;   __syncthreads();
;   {
;     const int dim = tid >> 1, half = tid & 1;
;     const float gd = p.gm_v_g[l * 256 + dim];
;     const unsigned short* src = (const unsigned short*)(p.ws + OFF_VT) + ((size_t)b * 256 + dim) * PTOK + pos0 + half * 64;
; #pragma unroll
;     for (int i = 0; i < 8; ++i) {
;       u32x4 w = *reinterpret_cast<const u32x4*>(src + i * 8);
;       const int t0 = half * 64 + i * 8;
;       float f0 = __uint_as_float(w[0] << 16) * rs[t0 + 0] * gd, f1 = __uint_as_float(w[0] & 0xffff0000u) * rs[t0 + 1] * gd;
;       float f2 = __uint_as_float(w[1] << 16) * rs[t0 + 2] * gd, f3 = __uint_as_float(w[1] & 0xffff0000u) * rs[t0 + 3] * gd;
;       float f4 = __uint_as_float(w[2] << 16) * rs[t0 + 4] * gd, f5 = __uint_as_float(w[2] & 0xffff0000u) * rs[t0 + 5] * gd;
;       float f6 = __uint_as_float(w[3] << 16) * rs[t0 + 6] * gd, f7 = __uint_as_float(w[3] & 0xffff0000u) * rs[t0 + 7] * gd;
;       u32x4 o = {cvtpk(f0, f1), cvtpk(f2, f3), cvtpk(f4, f5), cvtpk(f6, f7)};
;       *reinterpret_cast<u32x4*>(Vn + dim * 136 + t0) = o;
;     }
;   }
.LBB0_825:
	s_or_b64 exec, exec, s[6:7]
	s_or_b32 s6, s9, 0x2000
	s_and_b64 s[4:5], s[4:5], exec
	v_ashrrev_i32_e32 v34, 1, v20
	s_cselect_b32 s6, s9, s6
	v_ashrrev_i32_e32 v35, 31, v34
	s_lshl_b64 s[4:5], s[88:89], 8
	v_lshl_add_u64 v[18:19], s[4:5], 0, v[34:35]
	v_readlane_b32 s4, v255, 34
	v_readlane_b32 s5, v255, 35
	s_movk_i32 s7, 0x4200
	v_lshlrev_b32_e32 v16, 6, v20
	v_mov_b64_e32 v[22:23], s[4:5]
	v_mad_u64_u32 v[22:23], s[4:5], v18, s7, v[22:23]
	v_mad_i32_i24 v23, v19, s7, v23
	s_lshl_b32 s88, s6, 1
	v_and_b32_e32 v21, 64, v16
	v_lshl_add_u64 v[18:19], v[22:23], 0, s[88:89]
	v_lshlrev_b32_e32 v16, 1, v21
	v_lshl_add_u64 v[18:19], v[18:19], 0, v[16:17]
	s_waitcnt lgkmcnt(0)
	s_barrier
	global_load_dwordx4 v[22:25], v[18:19], off
	s_load_dwordx2 s[6:7], s[86:87], 0x58
	s_load_dwordx2 s[4:5], s[86:87], 0x68
	v_lshl_add_u32 v36, v21, 2, 0
	v_ashrrev_i32_e32 v70, 7, v20
	v_ashrrev_i32_e32 v71, 31, v70
	s_waitcnt lgkmcnt(0)
	v_lshl_add_u64 v[26:27], v[34:35], 2, s[6:7]
	global_load_dword v35, v[26:27], off
	ds_read_b128 v[26:29], v36
	ds_read_b128 v[30:33], v36 offset:16
	s_movk_i32 s6, 0x110
	v_readlane_b32 s10, v255, 36
	v_bfe_u32 v73, v20, 5, 1
	v_bfe_u32 v76, v20, 6, 1
	v_readlane_b32 s11, v255, 37
	v_mov_b32_e32 v79, v17
	s_waitcnt vmcnt(1)
	v_lshlrev_b32_e32 v21, 16, v22
	v_and_b32_e32 v22, 0xffff0000, v22
	v_lshlrev_b32_e32 v37, 16, v23
	v_and_b32_e32 v23, 0xffff0000, v23
	v_lshlrev_b32_e32 v38, 16, v24
	v_and_b32_e32 v24, 0xffff0000, v24
	v_lshlrev_b32_e32 v39, 16, v25
	v_and_b32_e32 v25, 0xffff0000, v25
	s_waitcnt lgkmcnt(1)
	v_mul_f32_e32 v21, v26, v21
	v_mul_f32_e32 v22, v27, v22
	v_mul_f32_e32 v26, v28, v37
	v_mul_f32_e32 v23, v29, v23
	s_waitcnt lgkmcnt(0)
	v_mul_f32_e32 v27, v30, v38
	v_mul_f32_e32 v24, v31, v24
	v_mul_f32_e32 v28, v32, v39
	v_mul_f32_e32 v25, v33, v25
	s_waitcnt vmcnt(0)
	v_mul_f32_e32 v22, v35, v22
	v_mul_f32_e32 v26, v35, v26
	v_mul_f32_e32 v23, v35, v23
	v_mul_f32_e32 v27, v35, v27
	v_mul_f32_e32 v24, v35, v24
	v_mul_f32_e32 v28, v35, v28
	v_mul_f32_e32 v25, v35, v25
	v_mul_f32_e32 v21, v35, v21
	v_cvt_pk_bf16_f32 v22, v21, v22
	v_cvt_pk_bf16_f32 v23, v26, v23
	v_cvt_pk_bf16_f32 v24, v27, v24
	v_cvt_pk_bf16_f32 v25, v28, v25
	global_load_dwordx4 v[26:29], v[18:19], off offset:16
	v_mul_lo_u32 v21, v34, s6
	v_add3_u32 v34, 0, v21, v16
	ds_write_b128 v34, v[22:25] offset:1024
	ds_read_b128 v[22:25], v36 offset:32
	ds_read_b128 v[30:33], v36 offset:48
	s_waitcnt vmcnt(0)
	v_lshlrev_b32_e32 v16, 16, v26
	v_and_b32_e32 v21, 0xffff0000, v26
	v_lshlrev_b32_e32 v26, 16, v27
	v_and_b32_e32 v27, 0xffff0000, v27
	v_lshlrev_b32_e32 v37, 16, v28
	v_and_b32_e32 v28, 0xffff0000, v28
	v_lshlrev_b32_e32 v38, 16, v29
	v_and_b32_e32 v29, 0xffff0000, v29
	s_waitcnt lgkmcnt(1)
	v_mul_f32_e32 v16, v22, v16
	v_mul_f32_e32 v21, v23, v21
	v_mul_f32_e32 v22, v24, v26
	v_mul_f32_e32 v23, v25, v27
	s_waitcnt lgkmcnt(0)
	v_mul_f32_e32 v24, v30, v37
	v_mul_f32_e32 v25, v31, v28
	v_mul_f32_e32 v26, v32, v38
	v_mul_f32_e32 v27, v33, v29
	v_mul_f32_e32 v28, v35, v22
	v_mul_f32_e32 v23, v35, v23
	v_mul_f32_e32 v24, v35, v24
	v_mul_f32_e32 v25, v35, v25
	v_mul_f32_e32 v26, v35, v26
	v_mul_f32_e32 v27, v35, v27
	v_mul_f32_e32 v16, v35, v16
	v_mul_f32_e32 v21, v35, v21
	v_cvt_pk_bf16_f32 v22, v16, v21
	v_cvt_pk_bf16_f32 v23, v28, v23
	v_cvt_pk_bf16_f32 v24, v24, v25
	v_cvt_pk_bf16_f32 v25, v26, v27
	global_load_dwordx4 v[26:29], v[18:19], off offset:32
	ds_write_b128 v34, v[22:25] offset:1040
	ds_read_b128 v[22:25], v36 offset:64
	ds_read_b128 v[30:33], v36 offset:80
	s_waitcnt vmcnt(0)
	v_lshlrev_b32_e32 v16, 16, v26
	v_and_b32_e32 v21, 0xffff0000, v26
	v_lshlrev_b32_e32 v26, 16, v27
	v_and_b32_e32 v27, 0xffff0000, v27
	v_lshlrev_b32_e32 v37, 16, v28
	v_and_b32_e32 v28, 0xffff0000, v28
	v_lshlrev_b32_e32 v38, 16, v29
	v_and_b32_e32 v29, 0xffff0000, v29
	s_waitcnt lgkmcnt(1)
	v_mul_f32_e32 v16, v22, v16
	v_mul_f32_e32 v21, v23, v21
	v_mul_f32_e32 v22, v24, v26
	v_mul_f32_e32 v23, v25, v27
	s_waitcnt lgkmcnt(0)
	v_mul_f32_e32 v24, v30, v37
	v_mul_f32_e32 v25, v31, v28
	v_mul_f32_e32 v26, v32, v38
	v_mul_f32_e32 v27, v33, v29
	v_mul_f32_e32 v28, v35, v22
	v_mul_f32_e32 v23, v35, v23
	v_mul_f32_e32 v24, v35, v24
	v_mul_f32_e32 v25, v35, v25
	v_mul_f32_e32 v26, v35, v26
	v_mul_f32_e32 v27, v35, v27
	v_mul_f32_e32 v16, v35, v16
	v_mul_f32_e32 v21, v35, v21
	v_cvt_pk_bf16_f32 v22, v16, v21
	v_cvt_pk_bf16_f32 v23, v28, v23
	v_cvt_pk_bf16_f32 v24, v24, v25
	v_cvt_pk_bf16_f32 v25, v26, v27
	global_load_dwordx4 v[26:29], v[18:19], off offset:48
	ds_write_b128 v34, v[22:25] offset:1056
	ds_read_b128 v[22:25], v36 offset:96
	ds_read_b128 v[30:33], v36 offset:112
	s_waitcnt vmcnt(0)
	v_lshlrev_b32_e32 v16, 16, v26
	v_and_b32_e32 v21, 0xffff0000, v26
	v_lshlrev_b32_e32 v26, 16, v27
	v_and_b32_e32 v27, 0xffff0000, v27
	v_lshlrev_b32_e32 v37, 16, v28
	v_and_b32_e32 v28, 0xffff0000, v28
	v_lshlrev_b32_e32 v38, 16, v29
	v_and_b32_e32 v29, 0xffff0000, v29
	s_waitcnt lgkmcnt(1)
	v_mul_f32_e32 v16, v22, v16
	v_mul_f32_e32 v21, v23, v21
	v_mul_f32_e32 v22, v24, v26
	v_mul_f32_e32 v23, v25, v27
	s_waitcnt lgkmcnt(0)
	v_mul_f32_e32 v24, v30, v37
	v_mul_f32_e32 v25, v31, v28
	v_mul_f32_e32 v26, v32, v38
	v_mul_f32_e32 v27, v33, v29
	v_mul_f32_e32 v28, v35, v22
	v_mul_f32_e32 v23, v35, v23
	v_mul_f32_e32 v24, v35, v24
	v_mul_f32_e32 v25, v35, v25
	v_mul_f32_e32 v26, v35, v26
	v_mul_f32_e32 v27, v35, v27
	v_mul_f32_e32 v16, v35, v16
	v_mul_f32_e32 v21, v35, v21
	v_cvt_pk_bf16_f32 v22, v16, v21
	v_cvt_pk_bf16_f32 v23, v28, v23
	v_cvt_pk_bf16_f32 v24, v24, v25
	v_cvt_pk_bf16_f32 v25, v26, v27
	global_load_dwordx4 v[26:29], v[18:19], off offset:64
	ds_write_b128 v34, v[22:25] offset:1072
	ds_read_b128 v[22:25], v36 offset:128
	ds_read_b128 v[30:33], v36 offset:144
	s_waitcnt vmcnt(0)
; __device__ __forceinline__ void gmlp_item(PARAMS_T& p, int l, int b, int pos0, int tokrow0) {
;     ...
;   {
;     const int dim = tid >> 1, half = tid & 1;
;     const float gd = p.gm_v_g[l * 256 + dim];
;     const unsigned short* src = (const unsigned short*)(p.ws + OFF_VT) + ((size_t)b * 256 + dim) * PTOK + pos0 + half * 64;
; #pragma unroll
;     for (int i = 0; i < 8; ++i) {
;       u32x4 w = *reinterpret_cast<const u32x4*>(src + i * 8);
;       const int t0 = half * 64 + i * 8;
;       float f0 = __uint_as_float(w[0] << 16) * rs[t0 + 0] * gd, f1 = __uint_as_float(w[0] & 0xffff0000u) * rs[t0 + 1] * gd;
;       float f2 = __uint_as_float(w[1] << 16) * rs[t0 + 2] * gd, f3 = __uint_as_float(w[1] & 0xffff0000u) * rs[t0 + 3] * gd;
;       float f4 = __uint_as_float(w[2] << 16) * rs[t0 + 4] * gd, f5 = __uint_as_float(w[2] & 0xffff0000u) * rs[t0 + 5] * gd;
;       float f6 = __uint_as_float(w[3] << 16) * rs[t0 + 6] * gd, f7 = __uint_as_float(w[3] & 0xffff0000u) * rs[t0 + 7] * gd;
;       u32x4 o = {cvtpk(f0, f1), cvtpk(f2, f3), cvtpk(f4, f5), cvtpk(f6, f7)};
;       *reinterpret_cast<u32x4*>(Vn + dim * 136 + t0) = o;
;     }
;   }
;   __syncthreads();
	v_lshlrev_b32_e32 v16, 16, v26
	v_and_b32_e32 v21, 0xffff0000, v26
	v_lshlrev_b32_e32 v26, 16, v27
	v_and_b32_e32 v27, 0xffff0000, v27
	v_lshlrev_b32_e32 v37, 16, v28
	v_and_b32_e32 v28, 0xffff0000, v28
	v_lshlrev_b32_e32 v38, 16, v29
	v_and_b32_e32 v29, 0xffff0000, v29
	s_waitcnt lgkmcnt(1)
	v_mul_f32_e32 v16, v22, v16
	v_mul_f32_e32 v21, v23, v21
	v_mul_f32_e32 v22, v24, v26
	v_mul_f32_e32 v23, v25, v27
	s_waitcnt lgkmcnt(0)
	v_mul_f32_e32 v24, v30, v37
	v_mul_f32_e32 v25, v31, v28
	v_mul_f32_e32 v26, v32, v38
	v_mul_f32_e32 v27, v33, v29
	v_mul_f32_e32 v28, v35, v22
	v_mul_f32_e32 v23, v35, v23
	v_mul_f32_e32 v24, v35, v24
	v_mul_f32_e32 v25, v35, v25
	v_mul_f32_e32 v26, v35, v26
	v_mul_f32_e32 v27, v35, v27
	v_mul_f32_e32 v16, v35, v16
	v_mul_f32_e32 v21, v35, v21
	v_cvt_pk_bf16_f32 v22, v16, v21
	v_cvt_pk_bf16_f32 v23, v28, v23
	v_cvt_pk_bf16_f32 v24, v24, v25
	v_cvt_pk_bf16_f32 v25, v26, v27
	global_load_dwordx4 v[26:29], v[18:19], off offset:80
	ds_write_b128 v34, v[22:25] offset:1088
	ds_read_b128 v[22:25], v36 offset:160
	ds_read_b128 v[30:33], v36 offset:176
	s_waitcnt vmcnt(0)
	v_lshlrev_b32_e32 v16, 16, v26
	v_and_b32_e32 v21, 0xffff0000, v26
	v_lshlrev_b32_e32 v26, 16, v27
	v_and_b32_e32 v27, 0xffff0000, v27
	v_lshlrev_b32_e32 v37, 16, v28
	v_and_b32_e32 v28, 0xffff0000, v28
	v_lshlrev_b32_e32 v38, 16, v29
	v_and_b32_e32 v29, 0xffff0000, v29
	s_waitcnt lgkmcnt(1)
	v_mul_f32_e32 v16, v22, v16
	v_mul_f32_e32 v21, v23, v21
	v_mul_f32_e32 v22, v24, v26
	v_mul_f32_e32 v23, v25, v27
	s_waitcnt lgkmcnt(0)
	v_mul_f32_e32 v24, v30, v37
	v_mul_f32_e32 v25, v31, v28
	v_mul_f32_e32 v26, v32, v38
	v_mul_f32_e32 v27, v33, v29
	v_mul_f32_e32 v28, v35, v22
	v_mul_f32_e32 v23, v35, v23
	v_mul_f32_e32 v24, v35, v24
	v_mul_f32_e32 v25, v35, v25
	v_mul_f32_e32 v26, v35, v26
	v_mul_f32_e32 v27, v35, v27
	v_mul_f32_e32 v16, v35, v16
	v_mul_f32_e32 v21, v35, v21
	v_cvt_pk_bf16_f32 v22, v16, v21
	v_cvt_pk_bf16_f32 v23, v28, v23
	v_cvt_pk_bf16_f32 v24, v24, v25
	v_cvt_pk_bf16_f32 v25, v26, v27
	global_load_dwordx4 v[26:29], v[18:19], off offset:96
	ds_write_b128 v34, v[22:25] offset:1104
	ds_read_b128 v[22:25], v36 offset:192
	ds_read_b128 v[30:33], v36 offset:208
	s_waitcnt vmcnt(0)
	v_lshlrev_b32_e32 v16, 16, v26
	v_and_b32_e32 v21, 0xffff0000, v26
	v_lshlrev_b32_e32 v26, 16, v27
	v_and_b32_e32 v27, 0xffff0000, v27
	v_lshlrev_b32_e32 v37, 16, v28
	v_and_b32_e32 v28, 0xffff0000, v28
	v_lshlrev_b32_e32 v38, 16, v29
	v_and_b32_e32 v29, 0xffff0000, v29
	s_waitcnt lgkmcnt(1)
	v_mul_f32_e32 v16, v22, v16
	v_mul_f32_e32 v21, v23, v21
	v_mul_f32_e32 v22, v24, v26
	v_mul_f32_e32 v23, v25, v27
	s_waitcnt lgkmcnt(0)
	v_mul_f32_e32 v24, v30, v37
	v_mul_f32_e32 v25, v31, v28
	v_mul_f32_e32 v26, v32, v38
	v_mul_f32_e32 v27, v33, v29
	v_mul_f32_e32 v28, v35, v22
	v_mul_f32_e32 v23, v35, v23
	v_mul_f32_e32 v24, v35, v24
	v_mul_f32_e32 v25, v35, v25
	v_mul_f32_e32 v26, v35, v26
	v_mul_f32_e32 v27, v35, v27
	v_mul_f32_e32 v16, v35, v16
	v_mul_f32_e32 v21, v35, v21
	v_cvt_pk_bf16_f32 v22, v16, v21
	v_cvt_pk_bf16_f32 v23, v28, v23
	v_cvt_pk_bf16_f32 v24, v24, v25
	v_cvt_pk_bf16_f32 v25, v26, v27
	global_load_dwordx4 v[26:29], v[18:19], off offset:112
	v_and_b32_e32 v30, 31, v20
	v_lshlrev_b32_e32 v16, 8, v30
	v_lshlrev_b64 v[18:19], 15, v[70:71]
	v_lshl_or_b32 v78, v76, 14, v16
	v_lshl_add_u64 v[18:19], s[10:11], 0, v[18:19]
	v_lshlrev_b32_e32 v16, 4, v73
	ds_write_b128 v34, v[22:25] offset:1120
	v_lshl_add_u64 v[80:81], v[18:19], 0, v[16:17]
	ds_read_b128 v[18:21], v36 offset:224
	ds_read_b128 v[22:25], v36 offset:240
	v_lshl_add_u64 v[74:75], v[80:81], 0, v[78:79]
	v_lshl_or_b32 v72, v70, 6, v30
	v_lshlrev_b64 v[70:71], 9, v[70:71]
	s_waitcnt vmcnt(0)
	v_lshlrev_b32_e32 v31, 16, v26
	v_and_b32_e32 v26, 0xffff0000, v26
	v_lshlrev_b32_e32 v32, 16, v27
	v_and_b32_e32 v27, 0xffff0000, v27
	v_lshlrev_b32_e32 v33, 16, v28
	v_and_b32_e32 v28, 0xffff0000, v28
	v_lshlrev_b32_e32 v36, 16, v29
	v_and_b32_e32 v29, 0xffff0000, v29
	s_waitcnt lgkmcnt(1)
	v_mul_f32_e32 v18, v18, v31
	v_mul_f32_e32 v19, v19, v26
	v_mul_f32_e32 v20, v20, v32
	v_mul_f32_e32 v21, v21, v27
	s_waitcnt lgkmcnt(0)
	v_mul_f32_e32 v22, v22, v33
	v_mul_f32_e32 v23, v23, v28
	v_mul_f32_e32 v24, v24, v36
	v_mul_f32_e32 v25, v25, v29
	v_mul_f32_e32 v18, v35, v18
	v_mul_f32_e32 v19, v35, v19
	v_mul_f32_e32 v20, v35, v20
	v_mul_f32_e32 v21, v35, v21
	v_mul_f32_e32 v22, v35, v22
	v_mul_f32_e32 v23, v35, v23
	v_mul_f32_e32 v24, v35, v24
	v_mul_f32_e32 v25, v35, v25
	v_cvt_pk_bf16_f32 v18, v18, v19
	v_cvt_pk_bf16_f32 v19, v20, v21
	v_cvt_pk_bf16_f32 v20, v22, v23
	v_cvt_pk_bf16_f32 v21, v24, v25
	ds_write_b128 v34, v[18:21] offset:1136
	s_waitcnt lgkmcnt(0)
	s_barrier
; __device__ __forceinline__ void gmlp_item(PARAMS_T& p, int l, int b, int pos0, int tokrow0) {
;     ...
;   const int g = wid >> 1, th = wid & 1;
;   const bf16* wsb = (const bf16*)(p.ws + OFF_WSBF) + ((size_t)l * 4 + g) * 128 * 128;
;   f32x16 acc[2][2] = {};
; #pragma unroll
;   for (int ks = 0; ks < 8; ++ks) {
;     bf16x8 af[2], bfr[2];
; #pragma unroll
;     for (int tb = 0; tb < 2; ++tb) af[tb] = *reinterpret_cast<const bf16x8*>(wsb + (size_t)(th * 64 + tb * 32 + r32) * 128 + ks * 16 + hi * 8);
; #pragma unroll
;     for (int db = 0; db < 2; ++db) bfr[db] = *reinterpret_cast<const bf16x8*>(Vn + (g * 64 + db * 32 + r32) * 136 + ks * 16 + hi * 8);
; #pragma unroll
;     for (int tb = 0; tb < 2; ++tb)
; #pragma unroll
;       for (int db = 0; db < 2; ++db) acc[tb][db] = __builtin_amdgcn_mfma_f32_32x32x16_bf16(af[tb], bfr[db], acc[tb][db], 0, 0, 0);
;   }
	v_and_b32_e32 v250, 31, v192
	v_bfe_u32 v251, v192, 5, 1
	v_lshrrev_b32_e32 v252, 7, v192
	v_bfe_u32 v253, v192, 6, 1
	v_lshl_or_b32 v254, v252, 6, v250
	v_lshlrev_b32_e32 v172, 1, v254
	v_mul_u32_u24_e32 v254, 0x110, v254
	v_lshl_add_u32 v254, v251, 4, v254
	v_add_u32_e32 v16, 0x400, v254
	v_lshl_or_b32 v254, v253, 6, v250
	v_lshlrev_b32_e32 v254, 8, v254
	v_lshl_or_b32 v254, v251, 4, v254
	v_lshl_add_u32 v254, v252, 15, v254
	v_mov_b32_e32 v162, v254
	v_mov_b32_e32 v163, 0
	v_lshl_add_u64 v[162:163], s[10:11], 0, v[162:163]
	v_mov_b32_e32 v164, 0x2000
	v_mov_b32_e32 v165, 0
	v_lshl_add_u64 v[164:165], v[162:163], 0, v[164:165]
	global_load_dwordx4 v[82:85], v[162:163], off
	global_load_dwordx4 v[86:89], v[164:165], off
	global_load_dwordx4 v[90:93], v[162:163], off offset:32
	global_load_dwordx4 v[94:97], v[164:165], off offset:32
	global_load_dwordx4 v[98:101], v[162:163], off offset:64
	global_load_dwordx4 v[102:105], v[164:165], off offset:64
	global_load_dwordx4 v[106:109], v[162:163], off offset:96
	global_load_dwordx4 v[110:113], v[164:165], off offset:96
	global_load_dwordx4 v[114:117], v[162:163], off offset:128
	global_load_dwordx4 v[118:121], v[164:165], off offset:128
	global_load_dwordx4 v[122:125], v[162:163], off offset:160
	global_load_dwordx4 v[126:129], v[164:165], off offset:160
	global_load_dwordx4 v[130:133], v[162:163], off offset:192
	global_load_dwordx4 v[134:137], v[164:165], off offset:192
	global_load_dwordx4 v[138:141], v[162:163], off offset:224
	global_load_dwordx4 v[142:145], v[164:165], off offset:224
	v_lshlrev_b32_e32 v171, 6, v253
	v_lshl_add_u32 v171, v251, 2, v171
	v_lshl_add_u32 v170, v252, 7, v171
	v_lshlrev_b32_e32 v170, 2, v170
	v_add_u32_e32 v171, s8, v171
	v_add_u32_e32 v254, 0, v171
	v_lshl_add_u32 v162, v254, 9, v172
	v_add_u32_e32 v254, 8, v171
	v_lshl_add_u32 v163, v254, 9, v172
	v_add_u32_e32 v254, 16, v171
	v_lshl_add_u32 v164, v254, 9, v172
	v_add_u32_e32 v254, 24, v171
	v_lshl_add_u32 v165, v254, 9, v172
	v_add_u32_e32 v254, 32, v171
	v_lshl_add_u32 v166, v254, 9, v172
	v_add_u32_e32 v254, 40, v171
	v_lshl_add_u32 v167, v254, 9, v172
	v_add_u32_e32 v254, 48, v171
	v_lshl_add_u32 v168, v254, 9, v172
	v_add_u32_e32 v254, 56, v171
	v_lshl_add_u32 v169, v254, 9, v172
	v_mov_b32_e32 v18, 0
	v_mov_b32_e32 v19, 0
	v_mov_b32_e32 v20, 0
	v_mov_b32_e32 v21, 0
	v_mov_b32_e32 v22, 0
	v_mov_b32_e32 v23, 0
	v_mov_b32_e32 v24, 0
	v_mov_b32_e32 v25, 0
	v_mov_b32_e32 v26, 0
	v_mov_b32_e32 v27, 0
	v_mov_b32_e32 v28, 0
	v_mov_b32_e32 v29, 0
	v_mov_b32_e32 v30, 0
	v_mov_b32_e32 v31, 0
	v_mov_b32_e32 v32, 0
	v_mov_b32_e32 v33, 0
	v_mov_b32_e32 v34, 0
	v_mov_b32_e32 v35, 0
	v_mov_b32_e32 v36, 0
	v_mov_b32_e32 v37, 0
	v_mov_b32_e32 v38, 0
	v_mov_b32_e32 v39, 0
	v_mov_b32_e32 v40, 0
	v_mov_b32_e32 v41, 0
	v_mov_b32_e32 v42, 0
	v_mov_b32_e32 v43, 0
	v_mov_b32_e32 v44, 0
	v_mov_b32_e32 v45, 0
	v_mov_b32_e32 v46, 0
	v_mov_b32_e32 v47, 0
	v_mov_b32_e32 v48, 0
	v_mov_b32_e32 v49, 0
	v_mov_b32_e32 v50, 0
	v_mov_b32_e32 v51, 0
	v_mov_b32_e32 v52, 0
	v_mov_b32_e32 v53, 0
	v_mov_b32_e32 v54, 0
	v_mov_b32_e32 v55, 0
	v_mov_b32_e32 v56, 0
	v_mov_b32_e32 v57, 0
	v_mov_b32_e32 v58, 0
	v_mov_b32_e32 v59, 0
	v_mov_b32_e32 v60, 0
	v_mov_b32_e32 v61, 0
	v_mov_b32_e32 v62, 0
	v_mov_b32_e32 v63, 0
	v_mov_b32_e32 v64, 0
	v_mov_b32_e32 v65, 0
	v_mov_b32_e32 v66, 0
	v_mov_b32_e32 v67, 0
	v_mov_b32_e32 v68, 0
	v_mov_b32_e32 v69, 0
	v_mov_b32_e32 v70, 0
	v_mov_b32_e32 v71, 0
	v_mov_b32_e32 v72, 0
	v_mov_b32_e32 v73, 0
	v_mov_b32_e32 v74, 0
	v_mov_b32_e32 v75, 0
	v_mov_b32_e32 v76, 0
	v_mov_b32_e32 v77, 0
	v_mov_b32_e32 v78, 0
	v_mov_b32_e32 v79, 0
	v_mov_b32_e32 v80, 0
	v_mov_b32_e32 v81, 0
	ds_read_b128 v[146:149], v16 offset:0
	ds_read_b128 v[150:153], v16 offset:8704
	ds_read_b128 v[154:157], v16 offset:32
	ds_read_b128 v[158:161], v16 offset:8736
	ds_read_b128 v[234:237], v16 offset:64
	ds_read_b128 v[238:241], v16 offset:8768
	ds_read_b128 v[242:245], v16 offset:96
	ds_read_b128 v[246:249], v16 offset:8800
	s_waitcnt vmcnt(15) lgkmcnt(7)
	v_mfma_f32_32x32x16_bf16 v[18:33], v[82:85], v[146:149], v[18:33]
	s_waitcnt vmcnt(15) lgkmcnt(6)
	v_mfma_f32_32x32x16_bf16 v[34:49], v[82:85], v[150:153], v[34:49]
	s_waitcnt vmcnt(14)
	v_mfma_f32_32x32x16_bf16 v[50:65], v[86:89], v[146:149], v[50:65]
	v_mfma_f32_32x32x16_bf16 v[66:81], v[86:89], v[150:153], v[66:81]
	s_waitcnt vmcnt(13) lgkmcnt(5)
	v_mfma_f32_32x32x16_bf16 v[18:33], v[90:93], v[154:157], v[18:33]
	s_waitcnt vmcnt(13) lgkmcnt(4)
	v_mfma_f32_32x32x16_bf16 v[34:49], v[90:93], v[158:161], v[34:49]
	s_waitcnt vmcnt(12)
	v_mfma_f32_32x32x16_bf16 v[50:65], v[94:97], v[154:157], v[50:65]
	v_mfma_f32_32x32x16_bf16 v[66:81], v[94:97], v[158:161], v[66:81]
	s_waitcnt vmcnt(11) lgkmcnt(3)
	v_mfma_f32_32x32x16_bf16 v[18:33], v[98:101], v[234:237], v[18:33]
	s_waitcnt vmcnt(11) lgkmcnt(2)
	v_mfma_f32_32x32x16_bf16 v[34:49], v[98:101], v[238:241], v[34:49]
	s_waitcnt vmcnt(10)
	v_mfma_f32_32x32x16_bf16 v[50:65], v[102:105], v[234:237], v[50:65]
	v_mfma_f32_32x32x16_bf16 v[66:81], v[102:105], v[238:241], v[66:81]
	s_waitcnt vmcnt(9) lgkmcnt(1)
	v_mfma_f32_32x32x16_bf16 v[18:33], v[106:109], v[242:245], v[18:33]
	s_waitcnt vmcnt(9) lgkmcnt(0)
	v_mfma_f32_32x32x16_bf16 v[34:49], v[106:109], v[246:249], v[34:49]
	s_waitcnt vmcnt(8)
; __device__ __forceinline__ unsigned short bf1(float a) { return (unsigned short)(cvtpk(a, 0.f) & 0xffffu); }
; __device__ __forceinline__ int crow(int r, int hi) { return (r & 3) + 8 * (r >> 2) + 4 * hi; }
; __device__ __forceinline__ void gmlp_item(PARAMS_T& p, int l, int b, int pos0, int tokrow0) {
;     ...
; #pragma unroll
;   for (int ks = 0; ks < 8; ++ks) {
;     bf16x8 af[2], bfr[2];
; #pragma unroll
;     for (int tb = 0; tb < 2; ++tb) af[tb] = *reinterpret_cast<const bf16x8*>(wsb + (size_t)(th * 64 + tb * 32 + r32) * 128 + ks * 16 + hi * 8);
; #pragma unroll
;     for (int db = 0; db < 2; ++db) bfr[db] = *reinterpret_cast<const bf16x8*>(Vn + (g * 64 + db * 32 + r32) * 136 + ks * 16 + hi * 8);
; #pragma unroll
;     for (int tb = 0; tb < 2; ++tb)
; #pragma unroll
;       for (int db = 0; db < 2; ++db) acc[tb][db] = __builtin_amdgcn_mfma_f32_32x32x16_bf16(af[tb], bfr[db], acc[tb][db], 0, 0, 0);
;   }
;   const float* bs = p.gm_bs + ((size_t)l * 4 + g) * 128;
;   const unsigned short* u = (const unsigned short*)(p.ws + OFF_U);
;   unsigned short* outp = (unsigned short*)(p.ws + OFF_ACTA);
; #pragma unroll
;   for (int tb = 0; tb < 2; ++tb)
; #pragma unroll
;     for (int r = 0; r < 16; ++r) {
;       const int t = th * 64 + tb * 32 + crow(r, hi);
;       const float bt = bs[t];
; #pragma unroll
;       for (int db = 0; db < 2; ++db) {
;         const int d = g * 64 + db * 32 + r32;
;         const float uv = __uint_as_float(((unsigned)u[(size_t)(tokrow0 + t) * 256 + d]) << 16);
;         outp[(size_t)(tokrow0 + t) * 1024 + 256 + d] = bf1(uv * (acc[tb][db][r] + bt));
;       }
;     }
	v_mfma_f32_32x32x16_bf16 v[50:65], v[110:113], v[242:245], v[50:65]
	v_mfma_f32_32x32x16_bf16 v[66:81], v[110:113], v[246:249], v[66:81]
	ds_read_b128 v[146:149], v16 offset:128
	ds_read_b128 v[150:153], v16 offset:8832
	ds_read_b128 v[154:157], v16 offset:160
	ds_read_b128 v[158:161], v16 offset:8864
	ds_read_b128 v[234:237], v16 offset:192
	ds_read_b128 v[238:241], v16 offset:8896
	ds_read_b128 v[242:245], v16 offset:224
	ds_read_b128 v[246:249], v16 offset:8928
	v_bfe_u32 v250, v192, 3, 3
	v_and_b32_e32 v251, 7, v192
	v_bfe_u32 v253, v192, 6, 1
	v_lshrrev_b32_e32 v254, 7, v192
	v_lshl_add_u32 v167, v253, 6, v250
	v_add_u32_e32 v167, s8, v167
	v_lshlrev_b32_e32 v168, 7, v254
	v_lshl_add_u32 v168, v251, 4, v168
	v_lshl_add_u32 v164, v167, 9, v168
	v_add_u32_e32 v167, 0x0, v164
	global_load_dwordx4 v[82:85], v167, s[80:81]
	v_add_u32_e32 v168, 0x1000, v164
	global_load_dwordx4 v[86:89], v168, s[80:81]
	v_add_u32_e32 v167, 0x2000, v164
	global_load_dwordx4 v[90:93], v167, s[80:81]
	v_add_u32_e32 v168, 0x3000, v164
	global_load_dwordx4 v[94:97], v168, s[80:81]
	v_add_u32_e32 v167, 0x4000, v164
	global_load_dwordx4 v[98:101], v167, s[80:81]
	v_add_u32_e32 v168, 0x5000, v164
	global_load_dwordx4 v[102:105], v168, s[80:81]
	v_add_u32_e32 v167, 0x6000, v164
	global_load_dwordx4 v[106:109], v167, s[80:81]
	v_add_u32_e32 v168, 0x7000, v164
	global_load_dwordx4 v[110:113], v168, s[80:81]
	s_waitcnt vmcnt(15) lgkmcnt(7)
	v_mfma_f32_32x32x16_bf16 v[18:33], v[114:117], v[146:149], v[18:33]
	s_waitcnt vmcnt(15) lgkmcnt(6)
	v_mfma_f32_32x32x16_bf16 v[34:49], v[114:117], v[150:153], v[34:49]
	s_waitcnt vmcnt(14)
	v_mfma_f32_32x32x16_bf16 v[50:65], v[118:121], v[146:149], v[50:65]
	v_mfma_f32_32x32x16_bf16 v[66:81], v[118:121], v[150:153], v[66:81]
	s_waitcnt vmcnt(13) lgkmcnt(5)
	v_mfma_f32_32x32x16_bf16 v[18:33], v[122:125], v[154:157], v[18:33]
	s_waitcnt vmcnt(13) lgkmcnt(4)
	v_mfma_f32_32x32x16_bf16 v[34:49], v[122:125], v[158:161], v[34:49]
	s_waitcnt vmcnt(12)
	v_mfma_f32_32x32x16_bf16 v[50:65], v[126:129], v[154:157], v[50:65]
	v_mfma_f32_32x32x16_bf16 v[66:81], v[126:129], v[158:161], v[66:81]
	s_waitcnt vmcnt(11) lgkmcnt(3)
	v_mfma_f32_32x32x16_bf16 v[18:33], v[130:133], v[234:237], v[18:33]
	s_waitcnt vmcnt(11) lgkmcnt(2)
	v_mfma_f32_32x32x16_bf16 v[34:49], v[130:133], v[238:241], v[34:49]
	s_waitcnt vmcnt(10)
	v_mfma_f32_32x32x16_bf16 v[50:65], v[134:137], v[234:237], v[50:65]
	v_mfma_f32_32x32x16_bf16 v[66:81], v[134:137], v[238:241], v[66:81]
	s_waitcnt vmcnt(9) lgkmcnt(1)
	v_mfma_f32_32x32x16_bf16 v[18:33], v[138:141], v[242:245], v[18:33]
	s_waitcnt vmcnt(9) lgkmcnt(0)
	v_mfma_f32_32x32x16_bf16 v[34:49], v[138:141], v[246:249], v[34:49]
	s_waitcnt vmcnt(8)
	v_mfma_f32_32x32x16_bf16 v[50:65], v[142:145], v[242:245], v[50:65]
	v_mfma_f32_32x32x16_bf16 v[66:81], v[142:145], v[246:249], v[66:81]
	v_bfe_u32 v250, v192, 3, 3
	v_and_b32_e32 v251, 7, v192
	v_bfe_u32 v253, v192, 6, 1
	v_lshrrev_b32_e32 v254, 7, v192
	v_lshl_add_u32 v167, v253, 6, v250
	v_lshl_add_u32 v166, v254, 7, v167
	v_lshlrev_b32_e32 v166, 2, v166
	v_add_u32_e32 v167, s8, v167
	v_lshlrev_b32_e32 v168, 7, v254
	v_lshl_add_u32 v168, v251, 4, v168
	v_lshl_add_u32 v164, v167, 9, v168
	v_lshl_add_u32 v165, v167, 11, v168
	global_load_dword v114, v166, s[4:5]
	global_load_dword v115, v166, s[4:5] offset:32
	global_load_dword v116, v166, s[4:5] offset:64
	global_load_dword v117, v166, s[4:5] offset:96
	global_load_dword v118, v166, s[4:5] offset:128
	global_load_dword v119, v166, s[4:5] offset:160
	global_load_dword v120, v166, s[4:5] offset:192
	global_load_dword v121, v166, s[4:5] offset:224
	v_lshrrev_b32_e32 v253, 6, v192
	v_mul_u32_u24_e32 v253, 0x1100, v253
	v_add_u32_e32 v253, 0x11800, v253
	v_mul_u32_u24_e32 v163, 0x110, v250
	v_lshl_add_u32 v163, v251, 5, v163
	v_add_u32_e32 v163, v253, v163
	v_and_b32_e32 v250, 31, v192
	v_bfe_u32 v251, v192, 5, 1
	v_mul_u32_u24_e32 v162, 0x440, v251
	v_lshl_add_u32 v162, v250, 2, v162
	v_add_u32_e32 v162, v253, v162
	ds_write_b32 v162, v18
	ds_write_b32 v162, v34 offset:128
	ds_write_b32 v162, v19 offset:272
	ds_write_b32 v162, v35 offset:400
	ds_write_b32 v162, v20 offset:544
	ds_write_b32 v162, v36 offset:672
	ds_write_b32 v162, v21 offset:816
	ds_write_b32 v162, v37 offset:944
	ds_write_b32 v162, v22 offset:2176
	ds_write_b32 v162, v38 offset:2304
	ds_write_b32 v162, v23 offset:2448
	ds_write_b32 v162, v39 offset:2576
	ds_write_b32 v162, v24 offset:2720
	ds_write_b32 v162, v40 offset:2848
	ds_write_b32 v162, v25 offset:2992
	ds_write_b32 v162, v41 offset:3120
	ds_read_b128 v[122:125], v163 offset:0
	ds_read_b128 v[126:129], v163 offset:16
	ds_read_b128 v[130:133], v163 offset:2176
	ds_read_b128 v[134:137], v163 offset:2192
	s_waitcnt vmcnt(0)
	s_waitcnt lgkmcnt(2)
	v_add_f32_e32 v252, v122, v114
	v_lshlrev_b32_e32 v253, 16, v82
	v_mul_f32_e32 v250, v252, v253
	v_add_f32_e32 v252, v123, v114
	v_and_b32_e32 v253, 0xffff0000, v82
	v_mul_f32_e32 v251, v252, v253
	v_cvt_pk_bf16_f32 v154, v250, v251
	v_add_f32_e32 v252, v124, v114
	v_lshlrev_b32_e32 v253, 16, v83
	v_mul_f32_e32 v250, v252, v253
	v_add_f32_e32 v252, v125, v114
	v_and_b32_e32 v253, 0xffff0000, v83
	v_mul_f32_e32 v251, v252, v253
	v_cvt_pk_bf16_f32 v155, v250, v251
	v_add_f32_e32 v252, v126, v114
	v_lshlrev_b32_e32 v253, 16, v84
	v_mul_f32_e32 v250, v252, v253
	v_add_f32_e32 v252, v127, v114
	v_and_b32_e32 v253, 0xffff0000, v84
	v_mul_f32_e32 v251, v252, v253
	v_cvt_pk_bf16_f32 v156, v250, v251
	v_add_f32_e32 v252, v128, v114
	v_lshlrev_b32_e32 v253, 16, v85
	v_mul_f32_e32 v250, v252, v253
	v_add_f32_e32 v252, v129, v114
	v_and_b32_e32 v253, 0xffff0000, v85
	v_mul_f32_e32 v251, v252, v253
	v_cvt_pk_bf16_f32 v157, v250, v251
	v_add_u32_e32 v167, 0x0, v165
	global_store_dwordx4 v167, v[154:157], s[0:1]
	s_waitcnt lgkmcnt(0)
; __device__ __forceinline__ unsigned short bf1(float a) { return (unsigned short)(cvtpk(a, 0.f) & 0xffffu); }
; __device__ __forceinline__ int crow(int r, int hi) { return (r & 3) + 8 * (r >> 2) + 4 * hi; }
; __device__ __forceinline__ void gmlp_item(PARAMS_T& p, int l, int b, int pos0, int tokrow0) {
;     ...
; #pragma unroll
;   for (int tb = 0; tb < 2; ++tb)
; #pragma unroll
;     for (int r = 0; r < 16; ++r) {
;       const int t = th * 64 + tb * 32 + crow(r, hi);
;       const float bt = bs[t];
; #pragma unroll
;       for (int db = 0; db < 2; ++db) {
;         const int d = g * 64 + db * 32 + r32;
;         const float uv = __uint_as_float(((unsigned)u[(size_t)(tokrow0 + t) * 256 + d]) << 16);
;         outp[(size_t)(tokrow0 + t) * 1024 + 256 + d] = bf1(uv * (acc[tb][db][r] + bt));
;       }
;     }
	v_add_f32_e32 v252, v130, v115
	v_lshlrev_b32_e32 v253, 16, v86
	v_mul_f32_e32 v250, v252, v253
	v_add_f32_e32 v252, v131, v115
	v_and_b32_e32 v253, 0xffff0000, v86
	v_mul_f32_e32 v251, v252, v253
	v_cvt_pk_bf16_f32 v158, v250, v251
	v_add_f32_e32 v252, v132, v115
	v_lshlrev_b32_e32 v253, 16, v87
	v_mul_f32_e32 v250, v252, v253
	v_add_f32_e32 v252, v133, v115
	v_and_b32_e32 v253, 0xffff0000, v87
	v_mul_f32_e32 v251, v252, v253
	v_cvt_pk_bf16_f32 v159, v250, v251
	v_add_f32_e32 v252, v134, v115
	v_lshlrev_b32_e32 v253, 16, v88
	v_mul_f32_e32 v250, v252, v253
	v_add_f32_e32 v252, v135, v115
	v_and_b32_e32 v253, 0xffff0000, v88
	v_mul_f32_e32 v251, v252, v253
	v_cvt_pk_bf16_f32 v160, v250, v251
	v_add_f32_e32 v252, v136, v115
	v_lshlrev_b32_e32 v253, 16, v89
	v_mul_f32_e32 v250, v252, v253
	v_add_f32_e32 v252, v137, v115
	v_and_b32_e32 v253, 0xffff0000, v89
	v_mul_f32_e32 v251, v252, v253
	v_cvt_pk_bf16_f32 v161, v250, v251
	v_add_u32_e32 v168, 0x4000, v165
	global_store_dwordx4 v168, v[158:161], s[0:1]
	ds_write_b32 v162, v26
	ds_write_b32 v162, v42 offset:128
	ds_write_b32 v162, v27 offset:272
	ds_write_b32 v162, v43 offset:400
	ds_write_b32 v162, v28 offset:544
	ds_write_b32 v162, v44 offset:672
	ds_write_b32 v162, v29 offset:816
	ds_write_b32 v162, v45 offset:944
	ds_write_b32 v162, v30 offset:2176
	ds_write_b32 v162, v46 offset:2304
	ds_write_b32 v162, v31 offset:2448
	ds_write_b32 v162, v47 offset:2576
	ds_write_b32 v162, v32 offset:2720
	ds_write_b32 v162, v48 offset:2848
	ds_write_b32 v162, v33 offset:2992
	ds_write_b32 v162, v49 offset:3120
	ds_read_b128 v[122:125], v163 offset:0
	ds_read_b128 v[126:129], v163 offset:16
	ds_read_b128 v[130:133], v163 offset:2176
	ds_read_b128 v[134:137], v163 offset:2192
	s_waitcnt lgkmcnt(2)
	v_add_f32_e32 v252, v122, v116
	v_lshlrev_b32_e32 v253, 16, v90
	v_mul_f32_e32 v250, v252, v253
	v_add_f32_e32 v252, v123, v116
	v_and_b32_e32 v253, 0xffff0000, v90
	v_mul_f32_e32 v251, v252, v253
	v_cvt_pk_bf16_f32 v154, v250, v251
	v_add_f32_e32 v252, v124, v116
	v_lshlrev_b32_e32 v253, 16, v91
	v_mul_f32_e32 v250, v252, v253
	v_add_f32_e32 v252, v125, v116
	v_and_b32_e32 v253, 0xffff0000, v91
	v_mul_f32_e32 v251, v252, v253
	v_cvt_pk_bf16_f32 v155, v250, v251
	v_add_f32_e32 v252, v126, v116
	v_lshlrev_b32_e32 v253, 16, v92
	v_mul_f32_e32 v250, v252, v253
	v_add_f32_e32 v252, v127, v116
	v_and_b32_e32 v253, 0xffff0000, v92
	v_mul_f32_e32 v251, v252, v253
	v_cvt_pk_bf16_f32 v156, v250, v251
	v_add_f32_e32 v252, v128, v116
	v_lshlrev_b32_e32 v253, 16, v93
	v_mul_f32_e32 v250, v252, v253
	v_add_f32_e32 v252, v129, v116
	v_and_b32_e32 v253, 0xffff0000, v93
	v_mul_f32_e32 v251, v252, v253
	v_cvt_pk_bf16_f32 v157, v250, v251
	v_add_u32_e32 v167, 0x8000, v165
	global_store_dwordx4 v167, v[154:157], s[0:1]
	s_waitcnt lgkmcnt(0)
	v_add_f32_e32 v252, v130, v117
	v_lshlrev_b32_e32 v253, 16, v94
	v_mul_f32_e32 v250, v252, v253
	v_add_f32_e32 v252, v131, v117
	v_and_b32_e32 v253, 0xffff0000, v94
	v_mul_f32_e32 v251, v252, v253
	v_cvt_pk_bf16_f32 v158, v250, v251
	v_add_f32_e32 v252, v132, v117
	v_lshlrev_b32_e32 v253, 16, v95
	v_mul_f32_e32 v250, v252, v253
	v_add_f32_e32 v252, v133, v117
	v_and_b32_e32 v253, 0xffff0000, v95
	v_mul_f32_e32 v251, v252, v253
	v_cvt_pk_bf16_f32 v159, v250, v251
	v_add_f32_e32 v252, v134, v117
	v_lshlrev_b32_e32 v253, 16, v96
	v_mul_f32_e32 v250, v252, v253
	v_add_f32_e32 v252, v135, v117
	v_and_b32_e32 v253, 0xffff0000, v96
	v_mul_f32_e32 v251, v252, v253
	v_cvt_pk_bf16_f32 v160, v250, v251
	v_add_f32_e32 v252, v136, v117
	v_lshlrev_b32_e32 v253, 16, v97
	v_mul_f32_e32 v250, v252, v253
	v_add_f32_e32 v252, v137, v117
	v_and_b32_e32 v253, 0xffff0000, v97
	v_mul_f32_e32 v251, v252, v253
	v_cvt_pk_bf16_f32 v161, v250, v251
	v_add_u32_e32 v168, 0xc000, v165
	global_store_dwordx4 v168, v[158:161], s[0:1]
	ds_write_b32 v162, v50
	ds_write_b32 v162, v66 offset:128
	ds_write_b32 v162, v51 offset:272
	ds_write_b32 v162, v67 offset:400
	ds_write_b32 v162, v52 offset:544
	ds_write_b32 v162, v68 offset:672
	ds_write_b32 v162, v53 offset:816
	ds_write_b32 v162, v69 offset:944
	ds_write_b32 v162, v54 offset:2176
	ds_write_b32 v162, v70 offset:2304
	ds_write_b32 v162, v55 offset:2448
	ds_write_b32 v162, v71 offset:2576
	ds_write_b32 v162, v56 offset:2720
	ds_write_b32 v162, v72 offset:2848
	ds_write_b32 v162, v57 offset:2992
	ds_write_b32 v162, v73 offset:3120
	ds_read_b128 v[122:125], v163 offset:0
	ds_read_b128 v[126:129], v163 offset:16
	ds_read_b128 v[130:133], v163 offset:2176
	ds_read_b128 v[134:137], v163 offset:2192
	s_waitcnt lgkmcnt(2)
; __device__ __forceinline__ unsigned short bf1(float a) { return (unsigned short)(cvtpk(a, 0.f) & 0xffffu); }
; __device__ __forceinline__ int crow(int r, int hi) { return (r & 3) + 8 * (r >> 2) + 4 * hi; }
; __device__ __forceinline__ void gmlp_item(PARAMS_T& p, int l, int b, int pos0, int tokrow0) {
;     ...
; #pragma unroll
;   for (int tb = 0; tb < 2; ++tb)
; #pragma unroll
;     for (int r = 0; r < 16; ++r) {
;       const int t = th * 64 + tb * 32 + crow(r, hi);
;       const float bt = bs[t];
; #pragma unroll
;       for (int db = 0; db < 2; ++db) {
;         const int d = g * 64 + db * 32 + r32;
;         const float uv = __uint_as_float(((unsigned)u[(size_t)(tokrow0 + t) * 256 + d]) << 16);
;         outp[(size_t)(tokrow0 + t) * 1024 + 256 + d] = bf1(uv * (acc[tb][db][r] + bt));
;       }
;     }
	v_add_f32_e32 v252, v122, v118
	v_lshlrev_b32_e32 v253, 16, v98
	v_mul_f32_e32 v250, v252, v253
	v_add_f32_e32 v252, v123, v118
	v_and_b32_e32 v253, 0xffff0000, v98
	v_mul_f32_e32 v251, v252, v253
	v_cvt_pk_bf16_f32 v154, v250, v251
	v_add_f32_e32 v252, v124, v118
	v_lshlrev_b32_e32 v253, 16, v99
	v_mul_f32_e32 v250, v252, v253
	v_add_f32_e32 v252, v125, v118
	v_and_b32_e32 v253, 0xffff0000, v99
	v_mul_f32_e32 v251, v252, v253
	v_cvt_pk_bf16_f32 v155, v250, v251
	v_add_f32_e32 v252, v126, v118
	v_lshlrev_b32_e32 v253, 16, v100
	v_mul_f32_e32 v250, v252, v253
	v_add_f32_e32 v252, v127, v118
	v_and_b32_e32 v253, 0xffff0000, v100
	v_mul_f32_e32 v251, v252, v253
	v_cvt_pk_bf16_f32 v156, v250, v251
	v_add_f32_e32 v252, v128, v118
	v_lshlrev_b32_e32 v253, 16, v101
	v_mul_f32_e32 v250, v252, v253
	v_add_f32_e32 v252, v129, v118
	v_and_b32_e32 v253, 0xffff0000, v101
	v_mul_f32_e32 v251, v252, v253
	v_cvt_pk_bf16_f32 v157, v250, v251
	v_add_u32_e32 v167, 0x10000, v165
	global_store_dwordx4 v167, v[154:157], s[0:1]
	s_waitcnt lgkmcnt(0)
	v_add_f32_e32 v252, v130, v119
	v_lshlrev_b32_e32 v253, 16, v102
	v_mul_f32_e32 v250, v252, v253
	v_add_f32_e32 v252, v131, v119
	v_and_b32_e32 v253, 0xffff0000, v102
	v_mul_f32_e32 v251, v252, v253
	v_cvt_pk_bf16_f32 v158, v250, v251
	v_add_f32_e32 v252, v132, v119
	v_lshlrev_b32_e32 v253, 16, v103
	v_mul_f32_e32 v250, v252, v253
	v_add_f32_e32 v252, v133, v119
	v_and_b32_e32 v253, 0xffff0000, v103
	v_mul_f32_e32 v251, v252, v253
	v_cvt_pk_bf16_f32 v159, v250, v251
	v_add_f32_e32 v252, v134, v119
	v_lshlrev_b32_e32 v253, 16, v104
	v_mul_f32_e32 v250, v252, v253
	v_add_f32_e32 v252, v135, v119
	v_and_b32_e32 v253, 0xffff0000, v104
	v_mul_f32_e32 v251, v252, v253
	v_cvt_pk_bf16_f32 v160, v250, v251
	v_add_f32_e32 v252, v136, v119
	v_lshlrev_b32_e32 v253, 16, v105
	v_mul_f32_e32 v250, v252, v253
	v_add_f32_e32 v252, v137, v119
	v_and_b32_e32 v253, 0xffff0000, v105
	v_mul_f32_e32 v251, v252, v253
	v_cvt_pk_bf16_f32 v161, v250, v251
	v_add_u32_e32 v168, 0x14000, v165
	global_store_dwordx4 v168, v[158:161], s[0:1]
	ds_write_b32 v162, v58
	ds_write_b32 v162, v74 offset:128
	ds_write_b32 v162, v59 offset:272
	ds_write_b32 v162, v75 offset:400
	ds_write_b32 v162, v60 offset:544
	ds_write_b32 v162, v76 offset:672
	ds_write_b32 v162, v61 offset:816
	ds_write_b32 v162, v77 offset:944
	ds_write_b32 v162, v62 offset:2176
	ds_write_b32 v162, v78 offset:2304
	ds_write_b32 v162, v63 offset:2448
	ds_write_b32 v162, v79 offset:2576
	ds_write_b32 v162, v64 offset:2720
	ds_write_b32 v162, v80 offset:2848
	ds_write_b32 v162, v65 offset:2992
	ds_write_b32 v162, v81 offset:3120
	ds_read_b128 v[122:125], v163 offset:0
	ds_read_b128 v[126:129], v163 offset:16
	ds_read_b128 v[130:133], v163 offset:2176
	ds_read_b128 v[134:137], v163 offset:2192
	s_waitcnt lgkmcnt(2)
	v_add_f32_e32 v252, v122, v120
	v_lshlrev_b32_e32 v253, 16, v106
	v_mul_f32_e32 v250, v252, v253
	v_add_f32_e32 v252, v123, v120
	v_and_b32_e32 v253, 0xffff0000, v106
	v_mul_f32_e32 v251, v252, v253
	v_cvt_pk_bf16_f32 v154, v250, v251
	v_add_f32_e32 v252, v124, v120
	v_lshlrev_b32_e32 v253, 16, v107
	v_mul_f32_e32 v250, v252, v253
	v_add_f32_e32 v252, v125, v120
	v_and_b32_e32 v253, 0xffff0000, v107
	v_mul_f32_e32 v251, v252, v253
	v_cvt_pk_bf16_f32 v155, v250, v251
	v_add_f32_e32 v252, v126, v120
	v_lshlrev_b32_e32 v253, 16, v108
	v_mul_f32_e32 v250, v252, v253
	v_add_f32_e32 v252, v127, v120
	v_and_b32_e32 v253, 0xffff0000, v108
	v_mul_f32_e32 v251, v252, v253
	v_cvt_pk_bf16_f32 v156, v250, v251
	v_add_f32_e32 v252, v128, v120
	v_lshlrev_b32_e32 v253, 16, v109
	v_mul_f32_e32 v250, v252, v253
	v_add_f32_e32 v252, v129, v120
	v_and_b32_e32 v253, 0xffff0000, v109
	v_mul_f32_e32 v251, v252, v253
	v_cvt_pk_bf16_f32 v157, v250, v251
	v_add_u32_e32 v167, 0x18000, v165
	global_store_dwordx4 v167, v[154:157], s[0:1]
	s_waitcnt lgkmcnt(0)
	v_add_f32_e32 v252, v130, v121
	v_lshlrev_b32_e32 v253, 16, v110
	v_mul_f32_e32 v250, v252, v253
	v_add_f32_e32 v252, v131, v121
	v_and_b32_e32 v253, 0xffff0000, v110
	v_mul_f32_e32 v251, v252, v253
	v_cvt_pk_bf16_f32 v158, v250, v251
	v_add_f32_e32 v252, v132, v121
	v_lshlrev_b32_e32 v253, 16, v111
	v_mul_f32_e32 v250, v252, v253
	v_add_f32_e32 v252, v133, v121
	v_and_b32_e32 v253, 0xffff0000, v111
	v_mul_f32_e32 v251, v252, v253
	v_cvt_pk_bf16_f32 v159, v250, v251
	v_add_f32_e32 v252, v134, v121
	v_lshlrev_b32_e32 v253, 16, v112
	v_mul_f32_e32 v250, v252, v253
	v_add_f32_e32 v252, v135, v121
	v_and_b32_e32 v253, 0xffff0000, v112
	v_mul_f32_e32 v251, v252, v253
	v_cvt_pk_bf16_f32 v160, v250, v251
	v_add_f32_e32 v252, v136, v121
	v_lshlrev_b32_e32 v253, 16, v113
	v_mul_f32_e32 v250, v252, v253
	v_add_f32_e32 v252, v137, v121
	v_and_b32_e32 v253, 0xffff0000, v113
	v_mul_f32_e32 v251, v252, v253
	v_cvt_pk_bf16_f32 v161, v250, v251
	v_add_u32_e32 v168, 0x1c000, v165
	global_store_dwordx4 v168, v[158:161], s[0:1]
	s_mov_b64 s[4:5], 0

; __device__ __forceinline__ void gmlp_item(PARAMS_T& p, int l, int b, int pos0, int tokrow0) {
;     ...
;   __syncthreads();
;   {
;     const int dim = tid >> 1, half = tid & 1;
;     const float gd = p.gm_v_g[l * 256 + dim];
;     const unsigned short* src = (const unsigned short*)(p.ws + OFF_VT) + ((size_t)b * 256 + dim) * PTOK + pos0 + half * 64;
; #pragma unroll
;     for (int i = 0; i < 8; ++i) {
;       u32x4 w = *reinterpret_cast<const u32x4*>(src + i * 8);
;       const int t0 = half * 64 + i * 8;
;       float f0 = __uint_as_float(w[0] << 16) * rs[t0 + 0] * gd, f1 = __uint_as_float(w[0] & 0xffff0000u) * rs[t0 + 1] * gd;
;       float f2 = __uint_as_float(w[1] << 16) * rs[t0 + 2] * gd, f3 = __uint_as_float(w[1] & 0xffff0000u) * rs[t0 + 3] * gd;
;       float f4 = __uint_as_float(w[2] << 16) * rs[t0 + 4] * gd, f5 = __uint_as_float(w[2] & 0xffff0000u) * rs[t0 + 5] * gd;
;       float f6 = __uint_as_float(w[3] << 16) * rs[t0 + 6] * gd, f7 = __uint_as_float(w[3] & 0xffff0000u) * rs[t0 + 7] * gd;
;       u32x4 o = {cvtpk(f0, f1), cvtpk(f2, f3), cvtpk(f4, f5), cvtpk(f6, f7)};
;       *reinterpret_cast<u32x4*>(Vn + dim * 136 + t0) = o;
;     }
;   }
.LBB0_1887:
	s_or_b64 exec, exec, s[6:7]
	v_ashrrev_i32_e32 v34, 1, v20
	v_ashrrev_i32_e32 v35, 31, v34
	s_lshl_b64 s[6:7], s[80:81], 8
	v_lshl_add_u64 v[18:19], s[6:7], 0, v[34:35]
	v_readlane_b32 s6, v255, 24
	v_readlane_b32 s7, v255, 25
	s_movk_i32 s5, 0x4200
	v_lshlrev_b32_e32 v16, 6, v20
	v_mov_b64_e32 v[22:23], s[6:7]
	v_mad_u64_u32 v[22:23], s[6:7], v18, s5, v[22:23]
	v_mad_i32_i24 v23, v19, s5, v23
	s_lshl_b32 s80, s4, 1
	v_and_b32_e32 v21, 64, v16
	v_lshl_add_u64 v[18:19], v[22:23], 0, s[80:81]
	v_lshlrev_b32_e32 v16, 1, v21
	v_lshl_add_u64 v[18:19], v[18:19], 0, v[16:17]
	s_waitcnt lgkmcnt(0)
	s_barrier
	global_load_dwordx4 v[22:25], v[18:19], off
	s_load_dwordx2 s[4:5], s[0:1], 0x58
	s_load_dwordx2 s[6:7], s[0:1], 0x68
	v_lshl_add_u32 v36, v21, 2, 0
	v_readlane_b32 s8, v255, 38
	v_bfe_u32 v73, v20, 5, 1
	s_waitcnt lgkmcnt(0)
	v_lshl_add_u64 v[26:27], v[34:35], 2, s[4:5]
	global_load_dword v35, v[26:27], off offset:1024
	ds_read_b128 v[26:29], v36
	ds_read_b128 v[30:33], v36 offset:16
	s_movk_i32 s4, 0x110
	v_bfe_u32 v76, v20, 6, 1
	v_readlane_b32 s9, v255, 39
	v_mov_b32_e32 v79, v17
	s_waitcnt vmcnt(1)
	v_lshlrev_b32_e32 v21, 16, v22
	v_and_b32_e32 v22, 0xffff0000, v22
	v_lshlrev_b32_e32 v37, 16, v23
	v_and_b32_e32 v23, 0xffff0000, v23
	v_lshlrev_b32_e32 v38, 16, v24
	v_and_b32_e32 v24, 0xffff0000, v24
	v_lshlrev_b32_e32 v39, 16, v25
	v_and_b32_e32 v25, 0xffff0000, v25
	s_waitcnt lgkmcnt(1)
	v_mul_f32_e32 v21, v26, v21
	v_mul_f32_e32 v22, v27, v22
	v_mul_f32_e32 v26, v28, v37
	v_mul_f32_e32 v23, v29, v23
	s_waitcnt lgkmcnt(0)
	v_mul_f32_e32 v27, v30, v38
	v_mul_f32_e32 v24, v31, v24
	v_mul_f32_e32 v28, v32, v39
	v_mul_f32_e32 v25, v33, v25
	s_waitcnt vmcnt(0)
	v_mul_f32_e32 v22, v35, v22
	v_mul_f32_e32 v26, v35, v26
	v_mul_f32_e32 v23, v35, v23
	v_mul_f32_e32 v27, v35, v27
	v_mul_f32_e32 v24, v35, v24
	v_mul_f32_e32 v28, v35, v28
	v_mul_f32_e32 v25, v35, v25
	v_mul_f32_e32 v21, v35, v21
	v_cvt_pk_bf16_f32 v22, v21, v22
	v_cvt_pk_bf16_f32 v23, v26, v23
	v_cvt_pk_bf16_f32 v24, v27, v24
	v_cvt_pk_bf16_f32 v25, v28, v25
	global_load_dwordx4 v[26:29], v[18:19], off offset:16
	v_mul_lo_u32 v21, v34, s4
	v_add3_u32 v34, 0, v21, v16
	ds_write_b128 v34, v[22:25] offset:1024
	ds_read_b128 v[22:25], v36 offset:32
	ds_read_b128 v[30:33], v36 offset:48
	s_waitcnt vmcnt(0)
	v_lshlrev_b32_e32 v16, 16, v26
	v_and_b32_e32 v21, 0xffff0000, v26
	v_lshlrev_b32_e32 v26, 16, v27
	v_and_b32_e32 v27, 0xffff0000, v27
	v_lshlrev_b32_e32 v37, 16, v28
	v_and_b32_e32 v28, 0xffff0000, v28
	v_lshlrev_b32_e32 v38, 16, v29
	v_and_b32_e32 v29, 0xffff0000, v29
	s_waitcnt lgkmcnt(1)
	v_mul_f32_e32 v16, v22, v16
	v_mul_f32_e32 v21, v23, v21
	v_mul_f32_e32 v22, v24, v26
	v_mul_f32_e32 v23, v25, v27
	s_waitcnt lgkmcnt(0)
	v_mul_f32_e32 v24, v30, v37
	v_mul_f32_e32 v25, v31, v28
	v_mul_f32_e32 v26, v32, v38
	v_mul_f32_e32 v27, v33, v29
	v_mul_f32_e32 v28, v35, v22
	v_mul_f32_e32 v23, v35, v23
	v_mul_f32_e32 v24, v35, v24
	v_mul_f32_e32 v25, v35, v25
	v_mul_f32_e32 v26, v35, v26
	v_mul_f32_e32 v27, v35, v27
	v_mul_f32_e32 v16, v35, v16
	v_mul_f32_e32 v21, v35, v21
	v_cvt_pk_bf16_f32 v22, v16, v21
	v_cvt_pk_bf16_f32 v23, v28, v23
	v_cvt_pk_bf16_f32 v24, v24, v25
	v_cvt_pk_bf16_f32 v25, v26, v27
	global_load_dwordx4 v[26:29], v[18:19], off offset:32
	ds_write_b128 v34, v[22:25] offset:1040
	ds_read_b128 v[22:25], v36 offset:64
	ds_read_b128 v[30:33], v36 offset:80
	s_waitcnt vmcnt(0)
	v_lshlrev_b32_e32 v16, 16, v26
	v_and_b32_e32 v21, 0xffff0000, v26
	v_lshlrev_b32_e32 v26, 16, v27
	v_and_b32_e32 v27, 0xffff0000, v27
	v_lshlrev_b32_e32 v37, 16, v28
	v_and_b32_e32 v28, 0xffff0000, v28
	v_lshlrev_b32_e32 v38, 16, v29
	v_and_b32_e32 v29, 0xffff0000, v29
	s_waitcnt lgkmcnt(1)
	v_mul_f32_e32 v16, v22, v16
	v_mul_f32_e32 v21, v23, v21
	v_mul_f32_e32 v22, v24, v26
	v_mul_f32_e32 v23, v25, v27
	s_waitcnt lgkmcnt(0)
	v_mul_f32_e32 v24, v30, v37
	v_mul_f32_e32 v25, v31, v28
	v_mul_f32_e32 v26, v32, v38
	v_mul_f32_e32 v27, v33, v29
	v_mul_f32_e32 v28, v35, v22
	v_mul_f32_e32 v23, v35, v23
	v_mul_f32_e32 v24, v35, v24
	v_mul_f32_e32 v25, v35, v25
	v_mul_f32_e32 v26, v35, v26
	v_mul_f32_e32 v27, v35, v27
	v_mul_f32_e32 v16, v35, v16
	v_mul_f32_e32 v21, v35, v21
	v_cvt_pk_bf16_f32 v22, v16, v21
	v_cvt_pk_bf16_f32 v23, v28, v23
	v_cvt_pk_bf16_f32 v24, v24, v25
	v_cvt_pk_bf16_f32 v25, v26, v27
	global_load_dwordx4 v[26:29], v[18:19], off offset:48
	ds_write_b128 v34, v[22:25] offset:1056
	ds_read_b128 v[22:25], v36 offset:96
	ds_read_b128 v[30:33], v36 offset:112
	s_waitcnt vmcnt(0)
	v_lshlrev_b32_e32 v16, 16, v26
	v_and_b32_e32 v21, 0xffff0000, v26
	v_lshlrev_b32_e32 v26, 16, v27
	v_and_b32_e32 v27, 0xffff0000, v27
	v_lshlrev_b32_e32 v37, 16, v28
	v_and_b32_e32 v28, 0xffff0000, v28
	v_lshlrev_b32_e32 v38, 16, v29
	v_and_b32_e32 v29, 0xffff0000, v29
	s_waitcnt lgkmcnt(1)
	v_mul_f32_e32 v16, v22, v16
	v_mul_f32_e32 v21, v23, v21
	v_mul_f32_e32 v22, v24, v26
	v_mul_f32_e32 v23, v25, v27
	s_waitcnt lgkmcnt(0)
	v_mul_f32_e32 v24, v30, v37
	v_mul_f32_e32 v25, v31, v28
	v_mul_f32_e32 v26, v32, v38
	v_mul_f32_e32 v27, v33, v29
	v_mul_f32_e32 v28, v35, v22
	v_mul_f32_e32 v23, v35, v23
	v_mul_f32_e32 v24, v35, v24
	v_mul_f32_e32 v25, v35, v25
	v_mul_f32_e32 v26, v35, v26
	v_mul_f32_e32 v27, v35, v27
	v_mul_f32_e32 v16, v35, v16
	v_mul_f32_e32 v21, v35, v21
	v_cvt_pk_bf16_f32 v22, v16, v21
	v_cvt_pk_bf16_f32 v23, v28, v23
	v_cvt_pk_bf16_f32 v24, v24, v25
	v_cvt_pk_bf16_f32 v25, v26, v27
	global_load_dwordx4 v[26:29], v[18:19], off offset:64
	ds_write_b128 v34, v[22:25] offset:1072
	ds_read_b128 v[22:25], v36 offset:128
	ds_read_b128 v[30:33], v36 offset:144
	s_waitcnt vmcnt(0)
; __device__ __forceinline__ void gmlp_item(PARAMS_T& p, int l, int b, int pos0, int tokrow0) {
;     ...
;   {
;     const int dim = tid >> 1, half = tid & 1;
;     const float gd = p.gm_v_g[l * 256 + dim];
;     const unsigned short* src = (const unsigned short*)(p.ws + OFF_VT) + ((size_t)b * 256 + dim) * PTOK + pos0 + half * 64;
; #pragma unroll
;     for (int i = 0; i < 8; ++i) {
;       u32x4 w = *reinterpret_cast<const u32x4*>(src + i * 8);
;       const int t0 = half * 64 + i * 8;
;       float f0 = __uint_as_float(w[0] << 16) * rs[t0 + 0] * gd, f1 = __uint_as_float(w[0] & 0xffff0000u) * rs[t0 + 1] * gd;
;       float f2 = __uint_as_float(w[1] << 16) * rs[t0 + 2] * gd, f3 = __uint_as_float(w[1] & 0xffff0000u) * rs[t0 + 3] * gd;
;       float f4 = __uint_as_float(w[2] << 16) * rs[t0 + 4] * gd, f5 = __uint_as_float(w[2] & 0xffff0000u) * rs[t0 + 5] * gd;
;       float f6 = __uint_as_float(w[3] << 16) * rs[t0 + 6] * gd, f7 = __uint_as_float(w[3] & 0xffff0000u) * rs[t0 + 7] * gd;
;       u32x4 o = {cvtpk(f0, f1), cvtpk(f2, f3), cvtpk(f4, f5), cvtpk(f6, f7)};
;       *reinterpret_cast<u32x4*>(Vn + dim * 136 + t0) = o;
;     }
;   }
;   __syncthreads();
	v_lshlrev_b32_e32 v16, 16, v26
	v_and_b32_e32 v21, 0xffff0000, v26
	v_lshlrev_b32_e32 v26, 16, v27
	v_and_b32_e32 v27, 0xffff0000, v27
	v_lshlrev_b32_e32 v37, 16, v28
	v_and_b32_e32 v28, 0xffff0000, v28
	v_lshlrev_b32_e32 v38, 16, v29
	v_and_b32_e32 v29, 0xffff0000, v29
	s_waitcnt lgkmcnt(1)
	v_mul_f32_e32 v16, v22, v16
	v_mul_f32_e32 v21, v23, v21
	v_mul_f32_e32 v22, v24, v26
	v_mul_f32_e32 v23, v25, v27
	s_waitcnt lgkmcnt(0)
	v_mul_f32_e32 v24, v30, v37
	v_mul_f32_e32 v25, v31, v28
	v_mul_f32_e32 v26, v32, v38
	v_mul_f32_e32 v27, v33, v29
	v_mul_f32_e32 v28, v35, v22
	v_mul_f32_e32 v23, v35, v23
	v_mul_f32_e32 v24, v35, v24
	v_mul_f32_e32 v25, v35, v25
	v_mul_f32_e32 v26, v35, v26
	v_mul_f32_e32 v27, v35, v27
	v_mul_f32_e32 v16, v35, v16
	v_mul_f32_e32 v21, v35, v21
	v_cvt_pk_bf16_f32 v22, v16, v21
	v_cvt_pk_bf16_f32 v23, v28, v23
	v_cvt_pk_bf16_f32 v24, v24, v25
	v_cvt_pk_bf16_f32 v25, v26, v27
	global_load_dwordx4 v[26:29], v[18:19], off offset:80
	ds_write_b128 v34, v[22:25] offset:1088
	ds_read_b128 v[22:25], v36 offset:160
	ds_read_b128 v[30:33], v36 offset:176
	s_waitcnt vmcnt(0)
	v_lshlrev_b32_e32 v16, 16, v26
	v_and_b32_e32 v21, 0xffff0000, v26
	v_lshlrev_b32_e32 v26, 16, v27
	v_and_b32_e32 v27, 0xffff0000, v27
	v_lshlrev_b32_e32 v37, 16, v28
	v_and_b32_e32 v28, 0xffff0000, v28
	v_lshlrev_b32_e32 v38, 16, v29
	v_and_b32_e32 v29, 0xffff0000, v29
	s_waitcnt lgkmcnt(1)
	v_mul_f32_e32 v16, v22, v16
	v_mul_f32_e32 v21, v23, v21
	v_mul_f32_e32 v22, v24, v26
	v_mul_f32_e32 v23, v25, v27
	s_waitcnt lgkmcnt(0)
	v_mul_f32_e32 v24, v30, v37
	v_mul_f32_e32 v25, v31, v28
	v_mul_f32_e32 v26, v32, v38
	v_mul_f32_e32 v27, v33, v29
	v_mul_f32_e32 v28, v35, v22
	v_mul_f32_e32 v23, v35, v23
	v_mul_f32_e32 v24, v35, v24
	v_mul_f32_e32 v25, v35, v25
	v_mul_f32_e32 v26, v35, v26
	v_mul_f32_e32 v27, v35, v27
	v_mul_f32_e32 v16, v35, v16
	v_mul_f32_e32 v21, v35, v21
	v_cvt_pk_bf16_f32 v22, v16, v21
	v_cvt_pk_bf16_f32 v23, v28, v23
	v_cvt_pk_bf16_f32 v24, v24, v25
	v_cvt_pk_bf16_f32 v25, v26, v27
	global_load_dwordx4 v[26:29], v[18:19], off offset:96
	ds_write_b128 v34, v[22:25] offset:1104
	ds_read_b128 v[22:25], v36 offset:192
	ds_read_b128 v[30:33], v36 offset:208
	s_waitcnt vmcnt(0)
	v_lshlrev_b32_e32 v16, 16, v26
	v_and_b32_e32 v21, 0xffff0000, v26
	v_lshlrev_b32_e32 v26, 16, v27
	v_and_b32_e32 v27, 0xffff0000, v27
	v_lshlrev_b32_e32 v37, 16, v28
	v_and_b32_e32 v28, 0xffff0000, v28
	v_lshlrev_b32_e32 v38, 16, v29
	v_and_b32_e32 v29, 0xffff0000, v29
	s_waitcnt lgkmcnt(1)
	v_mul_f32_e32 v16, v22, v16
	v_mul_f32_e32 v21, v23, v21
	v_mul_f32_e32 v22, v24, v26
	v_mul_f32_e32 v23, v25, v27
	s_waitcnt lgkmcnt(0)
	v_mul_f32_e32 v24, v30, v37
	v_mul_f32_e32 v25, v31, v28
	v_mul_f32_e32 v26, v32, v38
	v_mul_f32_e32 v27, v33, v29
	v_mul_f32_e32 v28, v35, v22
	v_mul_f32_e32 v23, v35, v23
	v_mul_f32_e32 v24, v35, v24
	v_mul_f32_e32 v25, v35, v25
	v_mul_f32_e32 v26, v35, v26
	v_mul_f32_e32 v27, v35, v27
	v_mul_f32_e32 v16, v35, v16
	v_mul_f32_e32 v21, v35, v21
	v_cvt_pk_bf16_f32 v22, v16, v21
	v_cvt_pk_bf16_f32 v23, v28, v23
	v_cvt_pk_bf16_f32 v24, v24, v25
	v_cvt_pk_bf16_f32 v25, v26, v27
	global_load_dwordx4 v[26:29], v[18:19], off offset:112
	v_ashrrev_i32_e32 v31, 7, v20
	v_add_u32_e32 v70, 4, v31
	v_and_b32_e32 v30, 31, v20
	v_ashrrev_i32_e32 v71, 31, v70
	v_lshlrev_b32_e32 v16, 8, v30
	v_lshlrev_b64 v[18:19], 15, v[70:71]
	v_lshl_or_b32 v78, v76, 14, v16
	v_lshl_add_u64 v[18:19], s[8:9], 0, v[18:19]
	v_lshlrev_b32_e32 v16, 4, v73
	ds_write_b128 v34, v[22:25] offset:1120
	v_lshl_add_u64 v[80:81], v[18:19], 0, v[16:17]
	ds_read_b128 v[18:21], v36 offset:224
	ds_read_b128 v[22:25], v36 offset:240
	v_lshl_add_u64 v[74:75], v[80:81], 0, v[78:79]
	v_lshl_or_b32 v72, v31, 6, v30
	v_lshlrev_b64 v[70:71], 9, v[70:71]
	s_waitcnt vmcnt(0)
	v_lshlrev_b32_e32 v32, 16, v26
	v_and_b32_e32 v26, 0xffff0000, v26
	v_lshlrev_b32_e32 v33, 16, v27
	v_and_b32_e32 v27, 0xffff0000, v27
	v_lshlrev_b32_e32 v36, 16, v28
	v_and_b32_e32 v28, 0xffff0000, v28
	v_lshlrev_b32_e32 v37, 16, v29
	v_and_b32_e32 v29, 0xffff0000, v29
	s_waitcnt lgkmcnt(1)
	v_mul_f32_e32 v18, v18, v32
	v_mul_f32_e32 v19, v19, v26
	v_mul_f32_e32 v20, v20, v33
	v_mul_f32_e32 v21, v21, v27
	s_waitcnt lgkmcnt(0)
	v_mul_f32_e32 v22, v22, v36
	v_mul_f32_e32 v23, v23, v28
	v_mul_f32_e32 v24, v24, v37
	v_mul_f32_e32 v25, v25, v29
	v_mul_f32_e32 v18, v35, v18
	v_mul_f32_e32 v19, v35, v19
	v_mul_f32_e32 v20, v35, v20
	v_mul_f32_e32 v21, v35, v21
	v_mul_f32_e32 v22, v35, v22
	v_mul_f32_e32 v23, v35, v23
	v_mul_f32_e32 v24, v35, v24
	v_mul_f32_e32 v25, v35, v25
	v_cvt_pk_bf16_f32 v18, v18, v19
	v_cvt_pk_bf16_f32 v19, v20, v21
	v_cvt_pk_bf16_f32 v20, v22, v23
	v_cvt_pk_bf16_f32 v21, v24, v25
	ds_write_b128 v34, v[18:21] offset:1136
	s_waitcnt lgkmcnt(0)
	s_barrier
; __device__ __forceinline__ void gmlp_item(PARAMS_T& p, int l, int b, int pos0, int tokrow0) {
;     ...
;   const int g = wid >> 1, th = wid & 1;
;   const bf16* wsb = (const bf16*)(p.ws + OFF_WSBF) + ((size_t)l * 4 + g) * 128 * 128;
;   f32x16 acc[2][2] = {};
; #pragma unroll
;   for (int ks = 0; ks < 8; ++ks) {
;     bf16x8 af[2], bfr[2];
; #pragma unroll
;     for (int tb = 0; tb < 2; ++tb) af[tb] = *reinterpret_cast<const bf16x8*>(wsb + (size_t)(th * 64 + tb * 32 + r32) * 128 + ks * 16 + hi * 8);
; #pragma unroll
;     for (int db = 0; db < 2; ++db) bfr[db] = *reinterpret_cast<const bf16x8*>(Vn + (g * 64 + db * 32 + r32) * 136 + ks * 16 + hi * 8);
; #pragma unroll
;     for (int tb = 0; tb < 2; ++tb)
; #pragma unroll
;       for (int db = 0; db < 2; ++db) acc[tb][db] = __builtin_amdgcn_mfma_f32_32x32x16_bf16(af[tb], bfr[db], acc[tb][db], 0, 0, 0);
;   }
	v_and_b32_e32 v250, 31, v192
	v_bfe_u32 v251, v192, 5, 1
	v_lshrrev_b32_e32 v252, 7, v192
	v_bfe_u32 v253, v192, 6, 1
	v_lshl_or_b32 v254, v252, 6, v250
	v_lshlrev_b32_e32 v172, 1, v254
	v_mul_u32_u24_e32 v254, 0x110, v254
	v_lshl_add_u32 v254, v251, 4, v254
	v_add_u32_e32 v16, 0x400, v254
	v_add_u32_e32 v252, 4, v252
	v_lshl_or_b32 v254, v253, 6, v250
	v_lshlrev_b32_e32 v254, 8, v254
	v_lshl_or_b32 v254, v251, 4, v254
	v_lshl_add_u32 v254, v252, 15, v254
	v_mov_b32_e32 v162, v254
	v_mov_b32_e32 v163, 0
	v_lshl_add_u64 v[162:163], s[8:9], 0, v[162:163]
	v_mov_b32_e32 v164, 0x2000
	v_mov_b32_e32 v165, 0
	v_lshl_add_u64 v[164:165], v[162:163], 0, v[164:165]
	global_load_dwordx4 v[82:85], v[162:163], off
	global_load_dwordx4 v[86:89], v[164:165], off
	global_load_dwordx4 v[90:93], v[162:163], off offset:32
	global_load_dwordx4 v[94:97], v[164:165], off offset:32
	global_load_dwordx4 v[98:101], v[162:163], off offset:64
	global_load_dwordx4 v[102:105], v[164:165], off offset:64
	global_load_dwordx4 v[106:109], v[162:163], off offset:96
	global_load_dwordx4 v[110:113], v[164:165], off offset:96
	global_load_dwordx4 v[114:117], v[162:163], off offset:128
	global_load_dwordx4 v[118:121], v[164:165], off offset:128
	global_load_dwordx4 v[122:125], v[162:163], off offset:160
	global_load_dwordx4 v[126:129], v[164:165], off offset:160
	global_load_dwordx4 v[130:133], v[162:163], off offset:192
	global_load_dwordx4 v[134:137], v[164:165], off offset:192
	global_load_dwordx4 v[138:141], v[162:163], off offset:224
	global_load_dwordx4 v[142:145], v[164:165], off offset:224
	v_lshlrev_b32_e32 v171, 6, v253
	v_lshl_add_u32 v171, v251, 2, v171
	v_lshl_add_u32 v170, v252, 7, v171
	v_lshlrev_b32_e32 v170, 2, v170
	v_add_u32_e32 v171, s3, v171
	v_add_u32_e32 v254, 0, v171
	v_lshl_add_u32 v162, v254, 9, v172
	v_add_u32_e32 v254, 8, v171
	v_lshl_add_u32 v163, v254, 9, v172
	v_add_u32_e32 v254, 16, v171
	v_lshl_add_u32 v164, v254, 9, v172
	v_add_u32_e32 v254, 24, v171
	v_lshl_add_u32 v165, v254, 9, v172
	v_add_u32_e32 v254, 32, v171
	v_lshl_add_u32 v166, v254, 9, v172
	v_add_u32_e32 v254, 40, v171
	v_lshl_add_u32 v167, v254, 9, v172
	v_add_u32_e32 v254, 48, v171
	v_lshl_add_u32 v168, v254, 9, v172
	v_add_u32_e32 v254, 56, v171
	v_lshl_add_u32 v169, v254, 9, v172
	v_mov_b32_e32 v18, 0
	v_mov_b32_e32 v19, 0
	v_mov_b32_e32 v20, 0
	v_mov_b32_e32 v21, 0
	v_mov_b32_e32 v22, 0
	v_mov_b32_e32 v23, 0
	v_mov_b32_e32 v24, 0
	v_mov_b32_e32 v25, 0
	v_mov_b32_e32 v26, 0
	v_mov_b32_e32 v27, 0
	v_mov_b32_e32 v28, 0
	v_mov_b32_e32 v29, 0
	v_mov_b32_e32 v30, 0
	v_mov_b32_e32 v31, 0
	v_mov_b32_e32 v32, 0
	v_mov_b32_e32 v33, 0
	v_mov_b32_e32 v34, 0
	v_mov_b32_e32 v35, 0
	v_mov_b32_e32 v36, 0
	v_mov_b32_e32 v37, 0
	v_mov_b32_e32 v38, 0
	v_mov_b32_e32 v39, 0
	v_mov_b32_e32 v40, 0
	v_mov_b32_e32 v41, 0
	v_mov_b32_e32 v42, 0
	v_mov_b32_e32 v43, 0
	v_mov_b32_e32 v44, 0
	v_mov_b32_e32 v45, 0
	v_mov_b32_e32 v46, 0
	v_mov_b32_e32 v47, 0
	v_mov_b32_e32 v48, 0
	v_mov_b32_e32 v49, 0
	v_mov_b32_e32 v50, 0
	v_mov_b32_e32 v51, 0
	v_mov_b32_e32 v52, 0
	v_mov_b32_e32 v53, 0
	v_mov_b32_e32 v54, 0
	v_mov_b32_e32 v55, 0
	v_mov_b32_e32 v56, 0
	v_mov_b32_e32 v57, 0
	v_mov_b32_e32 v58, 0
	v_mov_b32_e32 v59, 0
	v_mov_b32_e32 v60, 0
	v_mov_b32_e32 v61, 0
	v_mov_b32_e32 v62, 0
	v_mov_b32_e32 v63, 0
	v_mov_b32_e32 v64, 0
	v_mov_b32_e32 v65, 0
	v_mov_b32_e32 v66, 0
	v_mov_b32_e32 v67, 0
	v_mov_b32_e32 v68, 0
	v_mov_b32_e32 v69, 0
	v_mov_b32_e32 v70, 0
	v_mov_b32_e32 v71, 0
	v_mov_b32_e32 v72, 0
	v_mov_b32_e32 v73, 0
	v_mov_b32_e32 v74, 0
	v_mov_b32_e32 v75, 0
	v_mov_b32_e32 v76, 0
	v_mov_b32_e32 v77, 0
	v_mov_b32_e32 v78, 0
	v_mov_b32_e32 v79, 0
	v_mov_b32_e32 v80, 0
	v_mov_b32_e32 v81, 0
	ds_read_b128 v[146:149], v16 offset:0
	ds_read_b128 v[150:153], v16 offset:8704
	ds_read_b128 v[154:157], v16 offset:32
	ds_read_b128 v[158:161], v16 offset:8736
	ds_read_b128 v[234:237], v16 offset:64
	ds_read_b128 v[238:241], v16 offset:8768
	ds_read_b128 v[242:245], v16 offset:96
	ds_read_b128 v[246:249], v16 offset:8800
	s_waitcnt vmcnt(15) lgkmcnt(7)
	v_mfma_f32_32x32x16_bf16 v[18:33], v[82:85], v[146:149], v[18:33]
	s_waitcnt vmcnt(15) lgkmcnt(6)
	v_mfma_f32_32x32x16_bf16 v[34:49], v[82:85], v[150:153], v[34:49]
	s_waitcnt vmcnt(14)
	v_mfma_f32_32x32x16_bf16 v[50:65], v[86:89], v[146:149], v[50:65]
	v_mfma_f32_32x32x16_bf16 v[66:81], v[86:89], v[150:153], v[66:81]
	s_waitcnt vmcnt(13) lgkmcnt(5)
	v_mfma_f32_32x32x16_bf16 v[18:33], v[90:93], v[154:157], v[18:33]
	s_waitcnt vmcnt(13) lgkmcnt(4)
	v_mfma_f32_32x32x16_bf16 v[34:49], v[90:93], v[158:161], v[34:49]
	s_waitcnt vmcnt(12)
	v_mfma_f32_32x32x16_bf16 v[50:65], v[94:97], v[154:157], v[50:65]
	v_mfma_f32_32x32x16_bf16 v[66:81], v[94:97], v[158:161], v[66:81]
	s_waitcnt vmcnt(11) lgkmcnt(3)
	v_mfma_f32_32x32x16_bf16 v[18:33], v[98:101], v[234:237], v[18:33]
	s_waitcnt vmcnt(11) lgkmcnt(2)
	v_mfma_f32_32x32x16_bf16 v[34:49], v[98:101], v[238:241], v[34:49]
	s_waitcnt vmcnt(10)
	v_mfma_f32_32x32x16_bf16 v[50:65], v[102:105], v[234:237], v[50:65]
	v_mfma_f32_32x32x16_bf16 v[66:81], v[102:105], v[238:241], v[66:81]
	s_waitcnt vmcnt(9) lgkmcnt(1)
	v_mfma_f32_32x32x16_bf16 v[18:33], v[106:109], v[242:245], v[18:33]
	s_waitcnt vmcnt(9) lgkmcnt(0)
	v_mfma_f32_32x32x16_bf16 v[34:49], v[106:109], v[246:249], v[34:49]
	s_waitcnt vmcnt(8)
; __device__ __forceinline__ unsigned short bf1(float a) { return (unsigned short)(cvtpk(a, 0.f) & 0xffffu); }
; __device__ __forceinline__ int crow(int r, int hi) { return (r & 3) + 8 * (r >> 2) + 4 * hi; }
; __device__ __forceinline__ void gmlp_item(PARAMS_T& p, int l, int b, int pos0, int tokrow0) {
;     ...
; #pragma unroll
;   for (int ks = 0; ks < 8; ++ks) {
;     bf16x8 af[2], bfr[2];
; #pragma unroll
;     for (int tb = 0; tb < 2; ++tb) af[tb] = *reinterpret_cast<const bf16x8*>(wsb + (size_t)(th * 64 + tb * 32 + r32) * 128 + ks * 16 + hi * 8);
; #pragma unroll
;     for (int db = 0; db < 2; ++db) bfr[db] = *reinterpret_cast<const bf16x8*>(Vn + (g * 64 + db * 32 + r32) * 136 + ks * 16 + hi * 8);
; #pragma unroll
;     for (int tb = 0; tb < 2; ++tb)
; #pragma unroll
;       for (int db = 0; db < 2; ++db) acc[tb][db] = __builtin_amdgcn_mfma_f32_32x32x16_bf16(af[tb], bfr[db], acc[tb][db], 0, 0, 0);
;   }
;   const float* bs = p.gm_bs + ((size_t)l * 4 + g) * 128;
;   const unsigned short* u = (const unsigned short*)(p.ws + OFF_U);
;   unsigned short* outp = (unsigned short*)(p.ws + OFF_ACTA);
; #pragma unroll
;   for (int tb = 0; tb < 2; ++tb)
; #pragma unroll
;     for (int r = 0; r < 16; ++r) {
;       const int t = th * 64 + tb * 32 + crow(r, hi);
;       const float bt = bs[t];
; #pragma unroll
;       for (int db = 0; db < 2; ++db) {
;         const int d = g * 64 + db * 32 + r32;
;         const float uv = __uint_as_float(((unsigned)u[(size_t)(tokrow0 + t) * 256 + d]) << 16);
;         outp[(size_t)(tokrow0 + t) * 1024 + 256 + d] = bf1(uv * (acc[tb][db][r] + bt));
;       }
;     }
	v_mfma_f32_32x32x16_bf16 v[50:65], v[110:113], v[242:245], v[50:65]
	v_mfma_f32_32x32x16_bf16 v[66:81], v[110:113], v[246:249], v[66:81]
	ds_read_b128 v[146:149], v16 offset:128
	ds_read_b128 v[150:153], v16 offset:8832
	ds_read_b128 v[154:157], v16 offset:160
	ds_read_b128 v[158:161], v16 offset:8864
	ds_read_b128 v[234:237], v16 offset:192
	ds_read_b128 v[238:241], v16 offset:8896
	ds_read_b128 v[242:245], v16 offset:224
	ds_read_b128 v[246:249], v16 offset:8928
	v_bfe_u32 v250, v192, 3, 3
	v_and_b32_e32 v251, 7, v192
	v_bfe_u32 v253, v192, 6, 1
	v_lshrrev_b32_e32 v254, 7, v192
	v_lshl_add_u32 v167, v253, 6, v250
	v_add_u32_e32 v167, s3, v167
	v_lshlrev_b32_e32 v168, 7, v254
	v_lshl_add_u32 v168, v251, 4, v168
	v_lshl_add_u32 v164, v167, 9, v168
	v_add_u32_e32 v167, 0x0, v164
	global_load_dwordx4 v[82:85], v167, s[94:95]
	v_add_u32_e32 v168, 0x1000, v164
	global_load_dwordx4 v[86:89], v168, s[94:95]
	v_add_u32_e32 v167, 0x2000, v164
	global_load_dwordx4 v[90:93], v167, s[94:95]
	v_add_u32_e32 v168, 0x3000, v164
	global_load_dwordx4 v[94:97], v168, s[94:95]
	v_add_u32_e32 v167, 0x4000, v164
	global_load_dwordx4 v[98:101], v167, s[94:95]
	v_add_u32_e32 v168, 0x5000, v164
	global_load_dwordx4 v[102:105], v168, s[94:95]
	v_add_u32_e32 v167, 0x6000, v164
	global_load_dwordx4 v[106:109], v167, s[94:95]
	v_add_u32_e32 v168, 0x7000, v164
	global_load_dwordx4 v[110:113], v168, s[94:95]
	s_waitcnt vmcnt(15) lgkmcnt(7)
	v_mfma_f32_32x32x16_bf16 v[18:33], v[114:117], v[146:149], v[18:33]
	s_waitcnt vmcnt(15) lgkmcnt(6)
	v_mfma_f32_32x32x16_bf16 v[34:49], v[114:117], v[150:153], v[34:49]
	s_waitcnt vmcnt(14)
	v_mfma_f32_32x32x16_bf16 v[50:65], v[118:121], v[146:149], v[50:65]
	v_mfma_f32_32x32x16_bf16 v[66:81], v[118:121], v[150:153], v[66:81]
	s_waitcnt vmcnt(13) lgkmcnt(5)
	v_mfma_f32_32x32x16_bf16 v[18:33], v[122:125], v[154:157], v[18:33]
	s_waitcnt vmcnt(13) lgkmcnt(4)
	v_mfma_f32_32x32x16_bf16 v[34:49], v[122:125], v[158:161], v[34:49]
	s_waitcnt vmcnt(12)
	v_mfma_f32_32x32x16_bf16 v[50:65], v[126:129], v[154:157], v[50:65]
	v_mfma_f32_32x32x16_bf16 v[66:81], v[126:129], v[158:161], v[66:81]
	s_waitcnt vmcnt(11) lgkmcnt(3)
	v_mfma_f32_32x32x16_bf16 v[18:33], v[130:133], v[234:237], v[18:33]
	s_waitcnt vmcnt(11) lgkmcnt(2)
	v_mfma_f32_32x32x16_bf16 v[34:49], v[130:133], v[238:241], v[34:49]
	s_waitcnt vmcnt(10)
	v_mfma_f32_32x32x16_bf16 v[50:65], v[134:137], v[234:237], v[50:65]
	v_mfma_f32_32x32x16_bf16 v[66:81], v[134:137], v[238:241], v[66:81]
	s_waitcnt vmcnt(9) lgkmcnt(1)
	v_mfma_f32_32x32x16_bf16 v[18:33], v[138:141], v[242:245], v[18:33]
	s_waitcnt vmcnt(9) lgkmcnt(0)
	v_mfma_f32_32x32x16_bf16 v[34:49], v[138:141], v[246:249], v[34:49]
	s_waitcnt vmcnt(8)
	v_mfma_f32_32x32x16_bf16 v[50:65], v[142:145], v[242:245], v[50:65]
	v_mfma_f32_32x32x16_bf16 v[66:81], v[142:145], v[246:249], v[66:81]
	v_bfe_u32 v250, v192, 3, 3
	v_and_b32_e32 v251, 7, v192
	v_bfe_u32 v253, v192, 6, 1
	v_lshrrev_b32_e32 v254, 7, v192
	v_lshl_add_u32 v167, v253, 6, v250
	v_lshl_add_u32 v166, v254, 7, v167
	v_add_u32_e32 v166, 512, v166
	v_lshlrev_b32_e32 v166, 2, v166
	v_add_u32_e32 v167, s3, v167
	v_lshlrev_b32_e32 v168, 7, v254
	v_lshl_add_u32 v168, v251, 4, v168
	v_lshl_add_u32 v164, v167, 9, v168
	v_lshl_add_u32 v165, v167, 11, v168
	global_load_dword v114, v166, s[6:7]
	global_load_dword v115, v166, s[6:7] offset:32
	global_load_dword v116, v166, s[6:7] offset:64
	global_load_dword v117, v166, s[6:7] offset:96
	global_load_dword v118, v166, s[6:7] offset:128
	global_load_dword v119, v166, s[6:7] offset:160
	global_load_dword v120, v166, s[6:7] offset:192
	global_load_dword v121, v166, s[6:7] offset:224
	v_lshrrev_b32_e32 v253, 6, v192
	v_mul_u32_u24_e32 v253, 0x1100, v253
	v_add_u32_e32 v253, 0x11800, v253
	v_mul_u32_u24_e32 v163, 0x110, v250
	v_lshl_add_u32 v163, v251, 5, v163
	v_add_u32_e32 v163, v253, v163
	v_and_b32_e32 v250, 31, v192
	v_bfe_u32 v251, v192, 5, 1
	v_mul_u32_u24_e32 v162, 0x440, v251
	v_lshl_add_u32 v162, v250, 2, v162
	v_add_u32_e32 v162, v253, v162
	ds_write_b32 v162, v18
	ds_write_b32 v162, v34 offset:128
	ds_write_b32 v162, v19 offset:272
	ds_write_b32 v162, v35 offset:400
	ds_write_b32 v162, v20 offset:544
	ds_write_b32 v162, v36 offset:672
	ds_write_b32 v162, v21 offset:816
	ds_write_b32 v162, v37 offset:944
	ds_write_b32 v162, v22 offset:2176
	ds_write_b32 v162, v38 offset:2304
	ds_write_b32 v162, v23 offset:2448
	ds_write_b32 v162, v39 offset:2576
	ds_write_b32 v162, v24 offset:2720
	ds_write_b32 v162, v40 offset:2848
	ds_write_b32 v162, v25 offset:2992
	ds_write_b32 v162, v41 offset:3120
	ds_read_b128 v[122:125], v163 offset:0
	ds_read_b128 v[126:129], v163 offset:16
	ds_read_b128 v[130:133], v163 offset:2176
	ds_read_b128 v[134:137], v163 offset:2192
	s_waitcnt vmcnt(0)
	s_waitcnt lgkmcnt(2)
	v_add_f32_e32 v252, v122, v114
	v_lshlrev_b32_e32 v253, 16, v82
	v_mul_f32_e32 v250, v252, v253
	v_add_f32_e32 v252, v123, v114
	v_and_b32_e32 v253, 0xffff0000, v82
	v_mul_f32_e32 v251, v252, v253
	v_cvt_pk_bf16_f32 v154, v250, v251
	v_add_f32_e32 v252, v124, v114
	v_lshlrev_b32_e32 v253, 16, v83
	v_mul_f32_e32 v250, v252, v253
	v_add_f32_e32 v252, v125, v114
	v_and_b32_e32 v253, 0xffff0000, v83
	v_mul_f32_e32 v251, v252, v253
	v_cvt_pk_bf16_f32 v155, v250, v251
	v_add_f32_e32 v252, v126, v114
	v_lshlrev_b32_e32 v253, 16, v84
	v_mul_f32_e32 v250, v252, v253
	v_add_f32_e32 v252, v127, v114
	v_and_b32_e32 v253, 0xffff0000, v84
	v_mul_f32_e32 v251, v252, v253
	v_cvt_pk_bf16_f32 v156, v250, v251
	v_add_f32_e32 v252, v128, v114
	v_lshlrev_b32_e32 v253, 16, v85
	v_mul_f32_e32 v250, v252, v253
	v_add_f32_e32 v252, v129, v114
	v_and_b32_e32 v253, 0xffff0000, v85
	v_mul_f32_e32 v251, v252, v253
	v_cvt_pk_bf16_f32 v157, v250, v251
	v_add_u32_e32 v167, 0x0, v165
	global_store_dwordx4 v167, v[154:157], s[96:97]
	s_waitcnt lgkmcnt(0)
; __device__ __forceinline__ unsigned short bf1(float a) { return (unsigned short)(cvtpk(a, 0.f) & 0xffffu); }
; __device__ __forceinline__ int crow(int r, int hi) { return (r & 3) + 8 * (r >> 2) + 4 * hi; }
; __device__ __forceinline__ void gmlp_item(PARAMS_T& p, int l, int b, int pos0, int tokrow0) {
;     ...
; #pragma unroll
;   for (int tb = 0; tb < 2; ++tb)
; #pragma unroll
;     for (int r = 0; r < 16; ++r) {
;       const int t = th * 64 + tb * 32 + crow(r, hi);
;       const float bt = bs[t];
; #pragma unroll
;       for (int db = 0; db < 2; ++db) {
;         const int d = g * 64 + db * 32 + r32;
;         const float uv = __uint_as_float(((unsigned)u[(size_t)(tokrow0 + t) * 256 + d]) << 16);
;         outp[(size_t)(tokrow0 + t) * 1024 + 256 + d] = bf1(uv * (acc[tb][db][r] + bt));
;       }
;     }
	v_add_f32_e32 v252, v130, v115
	v_lshlrev_b32_e32 v253, 16, v86
	v_mul_f32_e32 v250, v252, v253
	v_add_f32_e32 v252, v131, v115
	v_and_b32_e32 v253, 0xffff0000, v86
	v_mul_f32_e32 v251, v252, v253
	v_cvt_pk_bf16_f32 v158, v250, v251
	v_add_f32_e32 v252, v132, v115
	v_lshlrev_b32_e32 v253, 16, v87
	v_mul_f32_e32 v250, v252, v253
	v_add_f32_e32 v252, v133, v115
	v_and_b32_e32 v253, 0xffff0000, v87
	v_mul_f32_e32 v251, v252, v253
	v_cvt_pk_bf16_f32 v159, v250, v251
	v_add_f32_e32 v252, v134, v115
	v_lshlrev_b32_e32 v253, 16, v88
	v_mul_f32_e32 v250, v252, v253
	v_add_f32_e32 v252, v135, v115
	v_and_b32_e32 v253, 0xffff0000, v88
	v_mul_f32_e32 v251, v252, v253
	v_cvt_pk_bf16_f32 v160, v250, v251
	v_add_f32_e32 v252, v136, v115
	v_lshlrev_b32_e32 v253, 16, v89
	v_mul_f32_e32 v250, v252, v253
	v_add_f32_e32 v252, v137, v115
	v_and_b32_e32 v253, 0xffff0000, v89
	v_mul_f32_e32 v251, v252, v253
	v_cvt_pk_bf16_f32 v161, v250, v251
	v_add_u32_e32 v168, 0x4000, v165
	global_store_dwordx4 v168, v[158:161], s[96:97]
	ds_write_b32 v162, v26
	ds_write_b32 v162, v42 offset:128
	ds_write_b32 v162, v27 offset:272
	ds_write_b32 v162, v43 offset:400
	ds_write_b32 v162, v28 offset:544
	ds_write_b32 v162, v44 offset:672
	ds_write_b32 v162, v29 offset:816
	ds_write_b32 v162, v45 offset:944
	ds_write_b32 v162, v30 offset:2176
	ds_write_b32 v162, v46 offset:2304
	ds_write_b32 v162, v31 offset:2448
	ds_write_b32 v162, v47 offset:2576
	ds_write_b32 v162, v32 offset:2720
	ds_write_b32 v162, v48 offset:2848
	ds_write_b32 v162, v33 offset:2992
	ds_write_b32 v162, v49 offset:3120
	ds_read_b128 v[122:125], v163 offset:0
	ds_read_b128 v[126:129], v163 offset:16
	ds_read_b128 v[130:133], v163 offset:2176
	ds_read_b128 v[134:137], v163 offset:2192
	s_waitcnt lgkmcnt(2)
	v_add_f32_e32 v252, v122, v116
	v_lshlrev_b32_e32 v253, 16, v90
	v_mul_f32_e32 v250, v252, v253
	v_add_f32_e32 v252, v123, v116
	v_and_b32_e32 v253, 0xffff0000, v90
	v_mul_f32_e32 v251, v252, v253
	v_cvt_pk_bf16_f32 v154, v250, v251
	v_add_f32_e32 v252, v124, v116
	v_lshlrev_b32_e32 v253, 16, v91
	v_mul_f32_e32 v250, v252, v253
	v_add_f32_e32 v252, v125, v116
	v_and_b32_e32 v253, 0xffff0000, v91
	v_mul_f32_e32 v251, v252, v253
	v_cvt_pk_bf16_f32 v155, v250, v251
	v_add_f32_e32 v252, v126, v116
	v_lshlrev_b32_e32 v253, 16, v92
	v_mul_f32_e32 v250, v252, v253
	v_add_f32_e32 v252, v127, v116
	v_and_b32_e32 v253, 0xffff0000, v92
	v_mul_f32_e32 v251, v252, v253
	v_cvt_pk_bf16_f32 v156, v250, v251
	v_add_f32_e32 v252, v128, v116
	v_lshlrev_b32_e32 v253, 16, v93
	v_mul_f32_e32 v250, v252, v253
	v_add_f32_e32 v252, v129, v116
	v_and_b32_e32 v253, 0xffff0000, v93
	v_mul_f32_e32 v251, v252, v253
	v_cvt_pk_bf16_f32 v157, v250, v251
	v_add_u32_e32 v167, 0x8000, v165
	global_store_dwordx4 v167, v[154:157], s[96:97]
	s_waitcnt lgkmcnt(0)
	v_add_f32_e32 v252, v130, v117
	v_lshlrev_b32_e32 v253, 16, v94
	v_mul_f32_e32 v250, v252, v253
	v_add_f32_e32 v252, v131, v117
	v_and_b32_e32 v253, 0xffff0000, v94
	v_mul_f32_e32 v251, v252, v253
	v_cvt_pk_bf16_f32 v158, v250, v251
	v_add_f32_e32 v252, v132, v117
	v_lshlrev_b32_e32 v253, 16, v95
	v_mul_f32_e32 v250, v252, v253
	v_add_f32_e32 v252, v133, v117
	v_and_b32_e32 v253, 0xffff0000, v95
	v_mul_f32_e32 v251, v252, v253
	v_cvt_pk_bf16_f32 v159, v250, v251
	v_add_f32_e32 v252, v134, v117
	v_lshlrev_b32_e32 v253, 16, v96
	v_mul_f32_e32 v250, v252, v253
	v_add_f32_e32 v252, v135, v117
	v_and_b32_e32 v253, 0xffff0000, v96
	v_mul_f32_e32 v251, v252, v253
	v_cvt_pk_bf16_f32 v160, v250, v251
	v_add_f32_e32 v252, v136, v117
	v_lshlrev_b32_e32 v253, 16, v97
	v_mul_f32_e32 v250, v252, v253
	v_add_f32_e32 v252, v137, v117
	v_and_b32_e32 v253, 0xffff0000, v97
	v_mul_f32_e32 v251, v252, v253
	v_cvt_pk_bf16_f32 v161, v250, v251
	v_add_u32_e32 v168, 0xc000, v165
	global_store_dwordx4 v168, v[158:161], s[96:97]
	ds_write_b32 v162, v50
	ds_write_b32 v162, v66 offset:128
	ds_write_b32 v162, v51 offset:272
	ds_write_b32 v162, v67 offset:400
	ds_write_b32 v162, v52 offset:544
	ds_write_b32 v162, v68 offset:672
	ds_write_b32 v162, v53 offset:816
	ds_write_b32 v162, v69 offset:944
	ds_write_b32 v162, v54 offset:2176
	ds_write_b32 v162, v70 offset:2304
	ds_write_b32 v162, v55 offset:2448
	ds_write_b32 v162, v71 offset:2576
	ds_write_b32 v162, v56 offset:2720
	ds_write_b32 v162, v72 offset:2848
	ds_write_b32 v162, v57 offset:2992
	ds_write_b32 v162, v73 offset:3120
	ds_read_b128 v[122:125], v163 offset:0
	ds_read_b128 v[126:129], v163 offset:16
	ds_read_b128 v[130:133], v163 offset:2176
	ds_read_b128 v[134:137], v163 offset:2192
	s_waitcnt lgkmcnt(2)
; __device__ __forceinline__ unsigned short bf1(float a) { return (unsigned short)(cvtpk(a, 0.f) & 0xffffu); }
; __device__ __forceinline__ int crow(int r, int hi) { return (r & 3) + 8 * (r >> 2) + 4 * hi; }
; __device__ __forceinline__ void gmlp_item(PARAMS_T& p, int l, int b, int pos0, int tokrow0) {
;     ...
;   const float* bs = p.gm_bs + ((size_t)l * 4 + g) * 128;
;   const unsigned short* u = (const unsigned short*)(p.ws + OFF_U);
;   unsigned short* outp = (unsigned short*)(p.ws + OFF_ACTA);
; #pragma unroll
;   for (int tb = 0; tb < 2; ++tb)
; #pragma unroll
;     for (int r = 0; r < 16; ++r) {
;       const int t = th * 64 + tb * 32 + crow(r, hi);
;       const float bt = bs[t];
; #pragma unroll
;       for (int db = 0; db < 2; ++db) {
;         const int d = g * 64 + db * 32 + r32;
;         const float uv = __uint_as_float(((unsigned)u[(size_t)(tokrow0 + t) * 256 + d]) << 16);
;         outp[(size_t)(tokrow0 + t) * 1024 + 256 + d] = bf1(uv * (acc[tb][db][r] + bt));
;       }
;     }
	v_add_f32_e32 v252, v122, v118
	v_lshlrev_b32_e32 v253, 16, v98
	v_mul_f32_e32 v250, v252, v253
	v_add_f32_e32 v252, v123, v118
	v_and_b32_e32 v253, 0xffff0000, v98
	v_mul_f32_e32 v251, v252, v253
	v_cvt_pk_bf16_f32 v154, v250, v251
	v_add_f32_e32 v252, v124, v118
	v_lshlrev_b32_e32 v253, 16, v99
	v_mul_f32_e32 v250, v252, v253
	v_add_f32_e32 v252, v125, v118
	v_and_b32_e32 v253, 0xffff0000, v99
	v_mul_f32_e32 v251, v252, v253
	v_cvt_pk_bf16_f32 v155, v250, v251
	v_add_f32_e32 v252, v126, v118
	v_lshlrev_b32_e32 v253, 16, v100
	v_mul_f32_e32 v250, v252, v253
	v_add_f32_e32 v252, v127, v118
	v_and_b32_e32 v253, 0xffff0000, v100
	v_mul_f32_e32 v251, v252, v253
	v_cvt_pk_bf16_f32 v156, v250, v251
	v_add_f32_e32 v252, v128, v118
	v_lshlrev_b32_e32 v253, 16, v101
	v_mul_f32_e32 v250, v252, v253
	v_add_f32_e32 v252, v129, v118
	v_and_b32_e32 v253, 0xffff0000, v101
	v_mul_f32_e32 v251, v252, v253
	v_cvt_pk_bf16_f32 v157, v250, v251
	v_add_u32_e32 v167, 0x10000, v165
	global_store_dwordx4 v167, v[154:157], s[96:97]
	s_waitcnt lgkmcnt(0)
	v_add_f32_e32 v252, v130, v119
	v_lshlrev_b32_e32 v253, 16, v102
	v_mul_f32_e32 v250, v252, v253
	v_add_f32_e32 v252, v131, v119
	v_and_b32_e32 v253, 0xffff0000, v102
	v_mul_f32_e32 v251, v252, v253
	v_cvt_pk_bf16_f32 v158, v250, v251
	v_add_f32_e32 v252, v132, v119
	v_lshlrev_b32_e32 v253, 16, v103
	v_mul_f32_e32 v250, v252, v253
	v_add_f32_e32 v252, v133, v119
	v_and_b32_e32 v253, 0xffff0000, v103
	v_mul_f32_e32 v251, v252, v253
	v_cvt_pk_bf16_f32 v159, v250, v251
	v_add_f32_e32 v252, v134, v119
	v_lshlrev_b32_e32 v253, 16, v104
	v_mul_f32_e32 v250, v252, v253
	v_add_f32_e32 v252, v135, v119
	v_and_b32_e32 v253, 0xffff0000, v104
	v_mul_f32_e32 v251, v252, v253
	v_cvt_pk_bf16_f32 v160, v250, v251
	v_add_f32_e32 v252, v136, v119
	v_lshlrev_b32_e32 v253, 16, v105
	v_mul_f32_e32 v250, v252, v253
	v_add_f32_e32 v252, v137, v119
	v_and_b32_e32 v253, 0xffff0000, v105
	v_mul_f32_e32 v251, v252, v253
	v_cvt_pk_bf16_f32 v161, v250, v251
	v_add_u32_e32 v168, 0x14000, v165
	global_store_dwordx4 v168, v[158:161], s[96:97]
	ds_write_b32 v162, v58
	ds_write_b32 v162, v74 offset:128
	ds_write_b32 v162, v59 offset:272
	ds_write_b32 v162, v75 offset:400
	ds_write_b32 v162, v60 offset:544
	ds_write_b32 v162, v76 offset:672
	ds_write_b32 v162, v61 offset:816
	ds_write_b32 v162, v77 offset:944
	ds_write_b32 v162, v62 offset:2176
	ds_write_b32 v162, v78 offset:2304
	ds_write_b32 v162, v63 offset:2448
	ds_write_b32 v162, v79 offset:2576
	ds_write_b32 v162, v64 offset:2720
	ds_write_b32 v162, v80 offset:2848
	ds_write_b32 v162, v65 offset:2992
	ds_write_b32 v162, v81 offset:3120
	ds_read_b128 v[122:125], v163 offset:0
	ds_read_b128 v[126:129], v163 offset:16
	ds_read_b128 v[130:133], v163 offset:2176
	ds_read_b128 v[134:137], v163 offset:2192
	s_waitcnt lgkmcnt(2)
	v_add_f32_e32 v252, v122, v120
	v_lshlrev_b32_e32 v253, 16, v106
	v_mul_f32_e32 v250, v252, v253
	v_add_f32_e32 v252, v123, v120
	v_and_b32_e32 v253, 0xffff0000, v106
	v_mul_f32_e32 v251, v252, v253
	v_cvt_pk_bf16_f32 v154, v250, v251
	v_add_f32_e32 v252, v124, v120
	v_lshlrev_b32_e32 v253, 16, v107
	v_mul_f32_e32 v250, v252, v253
	v_add_f32_e32 v252, v125, v120
	v_and_b32_e32 v253, 0xffff0000, v107
	v_mul_f32_e32 v251, v252, v253
	v_cvt_pk_bf16_f32 v155, v250, v251
	v_add_f32_e32 v252, v126, v120
	v_lshlrev_b32_e32 v253, 16, v108
	v_mul_f32_e32 v250, v252, v253
	v_add_f32_e32 v252, v127, v120
	v_and_b32_e32 v253, 0xffff0000, v108
	v_mul_f32_e32 v251, v252, v253
	v_cvt_pk_bf16_f32 v156, v250, v251
	v_add_f32_e32 v252, v128, v120
	v_lshlrev_b32_e32 v253, 16, v109
	v_mul_f32_e32 v250, v252, v253
	v_add_f32_e32 v252, v129, v120
	v_and_b32_e32 v253, 0xffff0000, v109
	v_mul_f32_e32 v251, v252, v253
	v_cvt_pk_bf16_f32 v157, v250, v251
	v_add_u32_e32 v167, 0x18000, v165
	global_store_dwordx4 v167, v[154:157], s[96:97]
	s_waitcnt lgkmcnt(0)
	v_add_f32_e32 v252, v130, v121
	v_lshlrev_b32_e32 v253, 16, v110
	v_mul_f32_e32 v250, v252, v253
	v_add_f32_e32 v252, v131, v121
	v_and_b32_e32 v253, 0xffff0000, v110
	v_mul_f32_e32 v251, v252, v253
	v_cvt_pk_bf16_f32 v158, v250, v251
	v_add_f32_e32 v252, v132, v121
	v_lshlrev_b32_e32 v253, 16, v111
	v_mul_f32_e32 v250, v252, v253
	v_add_f32_e32 v252, v133, v121
	v_and_b32_e32 v253, 0xffff0000, v111
	v_mul_f32_e32 v251, v252, v253
	v_cvt_pk_bf16_f32 v159, v250, v251
	v_add_f32_e32 v252, v134, v121
	v_lshlrev_b32_e32 v253, 16, v112
	v_mul_f32_e32 v250, v252, v253
	v_add_f32_e32 v252, v135, v121
	v_and_b32_e32 v253, 0xffff0000, v112
	v_mul_f32_e32 v251, v252, v253
	v_cvt_pk_bf16_f32 v160, v250, v251
	v_add_f32_e32 v252, v136, v121
	v_lshlrev_b32_e32 v253, 16, v113
	v_mul_f32_e32 v250, v252, v253
	v_add_f32_e32 v252, v137, v121
	v_and_b32_e32 v253, 0xffff0000, v113
	v_mul_f32_e32 v251, v252, v253
	v_cvt_pk_bf16_f32 v161, v250, v251
	v_add_u32_e32 v168, 0x1c000, v165
	global_store_dwordx4 v168, v[158:161], s[96:97]
	s_mov_b64 s[6:7], 0
